# attention loop: wave-level block-selection test via a precomputed scalar OR mask (2 VALU per step removed)
# baseline (speedup 1.0000x reference)
; DI void attn_phase(const Params& p, const int layer, const int wid_s) {
;     ...
;       unsigned kread[2][2], vread[4];
; #pragma unroll
;       for (int kt = 0; kt < 2; ++kt)
; #pragma unroll
;         for (int ks = 0; ks < 2; ++ks) { const int r = kt * 16 + fr, c = ks * 4 + fq; kread[kt][ks] = (unsigned)(r * 128 + ((c ^ (r & 7)) * 16)); }
; #pragma unroll
;       for (int dt = 0; dt < 4; ++dt) { const int r = dt * 16 + fr; vread[dt] = (unsigned)(4096 + r * 64 + ((fq ^ ((r >> 2) & 3)) * 16)); }
;     ...
;           if (br == 1 && kb + 31 + 128 <= t0 && __ballot((selmask >> (kb >> 6)) & 1u) == 0ull) continue;
.LBB0_349:
	v_add_u32_e32 v0, 0x19880, v185
	v_add_u32_e32 v64, 0x19880, v184
	v_add_u32_e32 v65, 0x19880, v183
	v_mov_b32_e32 v66, v244
	s_nop 1
	v_or_b32_dpp v116, v66, v66 quad_perm:[1,0,3,2] row_mask:0xf bank_mask:0xf
	s_nop 1
	v_or_b32_dpp v66, v116, v116 quad_perm:[2,3,0,1] row_mask:0xf bank_mask:0xf
	s_nop 1
	v_or_b32_dpp v116, v66, v66 row_half_mirror row_mask:0xf bank_mask:0xf
	s_nop 1
	v_or_b32_dpp v66, v116, v116 row_mirror row_mask:0xf bank_mask:0xf
	v_mov_b32_e32 v116, v66
	s_nop 1
	v_permlane16_swap_b32_e32 v66, v116
	v_or_b32_e32 v66, v66, v116
	v_mov_b32_e32 v116, v66
	s_nop 1
	v_permlane32_swap_b32_e32 v66, v116
	v_or_b32_e32 v66, v66, v116
	s_nop 0
	v_readfirstlane_b32 s39, v66
	s_and_b64 vcc, exec, s[30:31]
	s_cbranch_vccz .Lat_ytop
	s_branch .Lat_xtop

; template <bool SEL, bool GEN>
; DI void attn_step(const KF& kv, const int kb, const int t, const int lane, const bool selbit,
;                   const LAS float* tabh, const half8 (&q)[2][2], f32x4 (&O)[2][4], const float (&nR)[2], float (&l)[2]) {
;     ...
;   for (int hp = 0; hp < 2; ++hp) {
;     float nm = nR[hp];
;     if (SEL) nm = selbit ? nm : MASKV;
;     const f32x4 c0 = {nm, nm, nm, nm};
; #pragma unroll
;     for (int kt = 0; kt < 2; ++kt) {
;       s[hp][kt] = MFMA16(kv.k[kt][0], q[hp][0], c0);
;       s[hp][kt] = MFMA16(kv.k[kt][1], q[hp][1], s[hp][kt]);
;     }
;   }
;   if (GEN) {
;     const int d0 = t - kb - fq * 4;
; #pragma unroll
;     for (int kt = 0; kt < 2; ++kt)
; #pragma unroll
;       for (int j = 0; j < 4; ++j) {
;         const int dist = d0 - (kt * 16 + j);
;         const bool bad = SEL ? (dist < 0) : ((unsigned)dist >= 512u);
;         const int ix = bad ? 130 : (dist > 128 ? 128 : dist);
; #pragma unroll
;         for (int hp = 0; hp < 2; ++hp) s[hp][kt][j] += tabh[hp * 132 + ix];
;       }
;   }
;   half8 pf[2];
; #pragma unroll
;   for (int hp = 0; hp < 2; ++hp) {
;     f32x4 p0, p1;
; #pragma unroll
;     for (int j = 0; j < 4; ++j) { p0[j] = __builtin_amdgcn_exp2f(s[hp][0][j]); p1[j] = __builtin_amdgcn_exp2f(s[hp][1][j]); }
;     l[hp] += ((p0[0] + p0[1]) + (p0[2] + p0[3])) + ((p1[0] + p1[1]) + (p1[2] + p1[3]));
;     pf[hp] = pack8(p0, p1);
;   }
; #pragma unroll
;   for (int dt = 0; dt < 4; ++dt)
; #pragma unroll
;     for (int hp = 0; hp < 2; ++hp) O[hp][dt] = MFMA16(kv.v[dt], pf[hp], O[hp][dt]);
; DI void attn_phase(const Params& p, const int layer, const int wid_s) {
;     ...
;         asm volatile("s_waitcnt vmcnt(0)" ::: "memory");
;         __syncthreads();
;         RING_ISSUE(0); RING_ISSUE(1);
; #pragma unroll 1
;         for (int si = 0; si < nsteps; ++si) {
;           asm volatile("s_waitcnt vmcnt(1) lgkmcnt(0)" ::: "memory");
;           __builtin_amdgcn_s_barrier();
;           asm volatile("" ::: "memory");
;           RING_ISSUE(si + 2);
;           const int kb = kb0 + si * 32;
;           if (kb > kmax_w || kb < lo_w) continue;
;           if (br == 1 && kb + 31 + 128 <= t0 && __ballot((selmask >> (kb >> 6)) & 1u) == 0ull) continue;
;           LAS unsigned char* slotp = ring + (si % 3) * 8192;
;           KF kv;
; #pragma unroll
;           for (int kt = 0; kt < 2; ++kt)
; #pragma unroll
.Lat_noga_xa0:
	v_exp_f32_e32 v198, v100
	v_exp_f32_e32 v199, v101
	v_exp_f32_e32 v200, v102
	v_exp_f32_e32 v201, v103
	v_exp_f32_e32 v202, v104
	v_exp_f32_e32 v203, v105
	v_exp_f32_e32 v204, v106
	v_exp_f32_e32 v205, v107
	v_exp_f32_e32 v206, v108
	v_exp_f32_e32 v207, v109
	v_exp_f32_e32 v208, v110
	v_exp_f32_e32 v209, v111
	v_exp_f32_e32 v210, v112
	v_exp_f32_e32 v211, v113
	v_exp_f32_e32 v212, v114
	v_exp_f32_e32 v213, v115
	v_cvt_pkrtz_f16_f32 v120, v198, v199
	v_cvt_pkrtz_f16_f32 v121, v200, v201
	v_cvt_pkrtz_f16_f32 v122, v202, v203
	v_cvt_pkrtz_f16_f32 v123, v204, v205
	v_cvt_pkrtz_f16_f32 v124, v206, v207
	v_cvt_pkrtz_f16_f32 v125, v208, v209
	v_cvt_pkrtz_f16_f32 v126, v210, v211
	v_cvt_pkrtz_f16_f32 v127, v212, v213
	s_waitcnt lgkmcnt(0)
	s_and_b32 s44, s12, 2
	s_or_b32 s44, s44, 1
	v_mfma_f32_16x16x32_f16 v[100:103], v[96:99], v[8:11], v[128:131]
	s_add_i32 s8, s45, 64
	s_min_i32 s8, s8, s14
	s_mul_i32 s8, s8, s42
	v_mfma_f32_16x16x32_f16 v[104:107], v[88:91], v[8:11], v[128:131]
	s_mov_b32 s9, 0
	v_lshl_add_u64 v[238:239], v[240:241], 0, s[8:9]
	s_add_i32 m0, s22, 0x1d880
	s_nop 0
	v_mfma_f32_16x16x32_f16 v[108:111], v[96:99], v[16:19], v[132:135]
	global_load_lds_dwordx4 v[238:239], off
	s_add_i32 s45, s45, 32
	s_add_i32 s41, s41, -1
	v_mfma_f32_16x16x32_f16 v[112:115], v[88:91], v[16:19], v[132:135]
	s_add_i32 s10, s45, 0x9f
	s_cmp_gt_i32 s10, s51
	s_cselect_b32 s11, 2, 0
	s_add_i32 s10, s45, 0x1f1
	v_mfma_f32_16x16x32_f16 v[100:103], v[92:95], v[12:15], v[100:103]
	s_cmp_le_i32 s10, s51
	s_cselect_b32 s10, 2, 0
	s_and_b32 s10, s10, s4
	v_mfma_f32_16x16x32_f16 v[104:107], v[84:87], v[12:15], v[104:107]
	s_or_b32 s11, s11, s10
	s_lshr_b32 s10, s45, 6
	s_bitcmp1_b32 s39, s10
	s_cselect_b32 s10, 1, 0
	v_mfma_f32_16x16x32_f16 v[108:111], v[92:95], v[20:23], v[108:111]
	s_lshr_b32 s9, s11, 1
	s_or_b32 s10, s10, s9
	s_cmp_le_i32 s45, s15
	v_mfma_f32_16x16x32_f16 v[112:115], v[84:87], v[20:23], v[112:115]
	s_cselect_b32 s10, s10, 0
	s_cmp_ge_i32 s45, s40
	s_cselect_b32 s10, s10, 0
	s_or_b32 s12, s11, s10
	v_mfma_f32_16x16x32_f16 v[60:63], v[80:83], v[120:123], v[60:63]
	v_add_f32_e32 v214, v214, v198
	v_add_f32_e32 v215, v215, v199
	v_mfma_f32_16x16x32_f16 v[56:59], v[76:79], v[120:123], v[56:59]
	v_add_f32_e32 v216, v216, v200
	v_add_f32_e32 v217, v217, v201
	v_mfma_f32_16x16x32_f16 v[52:55], v[72:75], v[120:123], v[52:55]
	v_add_f32_e32 v214, v214, v202
	v_add_f32_e32 v215, v215, v203
	v_mfma_f32_16x16x32_f16 v[48:51], v[68:71], v[120:123], v[48:51]
	v_add_f32_e32 v216, v216, v204
	v_add_f32_e32 v217, v217, v205
	v_mfma_f32_16x16x32_f16 v[44:47], v[80:83], v[124:127], v[44:47]
	v_add_f32_e32 v218, v218, v206
	v_add_f32_e32 v219, v219, v207
	v_mfma_f32_16x16x32_f16 v[40:43], v[76:79], v[124:127], v[40:43]
	v_add_f32_e32 v220, v220, v208
	v_add_f32_e32 v221, v221, v209
	v_mfma_f32_16x16x32_f16 v[36:39], v[72:75], v[124:127], v[36:39]
	v_add_f32_e32 v218, v218, v210
	v_add_f32_e32 v219, v219, v211
	v_mfma_f32_16x16x32_f16 v[32:35], v[68:71], v[124:127], v[32:35]
	v_add_f32_e32 v220, v220, v212
	v_add_f32_e32 v221, v221, v213
	ds_read_b128 v[80:83], v65 offset:4096
	ds_read_b128 v[76:79], v65 offset:5120
	ds_read_b128 v[72:75], v65 offset:6144
	ds_read_b128 v[68:71], v65 offset:7168
	s_cmp_lg_u32 s41, 0
	s_cbranch_scc1 .Lat_xtop1
	s_branch .Lat_xexit
.Lat_xb0:
	s_waitcnt lgkmcnt(0)
	s_and_b32 s44, s12, 2
	s_or_b32 s44, s44, 1
	v_mfma_f32_16x16x32_f16 v[100:103], v[96:99], v[8:11], v[128:131]
	s_add_i32 s8, s45, 64
	s_min_i32 s8, s8, s14
	s_mul_i32 s8, s8, s42
	v_mfma_f32_16x16x32_f16 v[104:107], v[88:91], v[8:11], v[128:131]
	s_mov_b32 s9, 0
	v_lshl_add_u64 v[238:239], v[240:241], 0, s[8:9]
	s_add_i32 m0, s22, 0x1d880
	s_nop 0
	v_mfma_f32_16x16x32_f16 v[108:111], v[96:99], v[16:19], v[132:135]
	global_load_lds_dwordx4 v[238:239], off
	s_add_i32 s45, s45, 32
	s_add_i32 s41, s41, -1
	v_mfma_f32_16x16x32_f16 v[112:115], v[88:91], v[16:19], v[132:135]
	s_add_i32 s10, s45, 0x9f
	s_cmp_gt_i32 s10, s51
	s_cselect_b32 s11, 2, 0
	s_add_i32 s10, s45, 0x1f1
	v_mfma_f32_16x16x32_f16 v[100:103], v[92:95], v[12:15], v[100:103]
	s_cmp_le_i32 s10, s51
	s_cselect_b32 s10, 2, 0
	s_and_b32 s10, s10, s4
	v_mfma_f32_16x16x32_f16 v[104:107], v[84:87], v[12:15], v[104:107]
	s_or_b32 s11, s11, s10
	s_lshr_b32 s10, s45, 6
	s_bitcmp1_b32 s39, s10
	s_cselect_b32 s10, 1, 0
	v_mfma_f32_16x16x32_f16 v[108:111], v[92:95], v[20:23], v[108:111]
	s_lshr_b32 s9, s11, 1
	s_or_b32 s10, s10, s9
	s_cmp_le_i32 s45, s15
	v_mfma_f32_16x16x32_f16 v[112:115], v[84:87], v[20:23], v[112:115]
	s_cselect_b32 s10, s10, 0
	s_cmp_ge_i32 s45, s40
	s_cselect_b32 s10, s10, 0
	s_or_b32 s12, s11, s10
	ds_read_b128 v[80:83], v65 offset:4096
	ds_read_b128 v[76:79], v65 offset:5120
	ds_read_b128 v[72:75], v65 offset:6144
	ds_read_b128 v[68:71], v65 offset:7168
	s_cmp_lg_u32 s41, 0
	s_cbranch_scc1 .Lat_xtop1
	s_branch .Lat_xexit

; #define MFMA16(a, b, c) __builtin_amdgcn_mfma_f32_16x16x32_f16((a), (b), (c), 0, 0, 0)
; #define LAS __attribute__((address_space(3)))
; template <bool SEL, bool GEN>
; DI void attn_step(const KF& kv, const int kb, const int t, const int lane, const bool selbit,
;                   const LAS float* tabh, const half8 (&q)[2][2], f32x4 (&O)[2][4], const float (&nR)[2], float (&l)[2]) {
;     ...
;     for (int j = 0; j < 4; ++j) { p0[j] = __builtin_amdgcn_exp2f(s[hp][0][j]); p1[j] = __builtin_amdgcn_exp2f(s[hp][1][j]); }
;     l[hp] += ((p0[0] + p0[1]) + (p0[2] + p0[3])) + ((p1[0] + p1[1]) + (p1[2] + p1[3]));
;     pf[hp] = pack8(p0, p1);
;   }
; #pragma unroll
;   for (int dt = 0; dt < 4; ++dt)
; #pragma unroll
;     for (int hp = 0; hp < 2; ++hp) O[hp][dt] = MFMA16(kv.v[dt], pf[hp], O[hp][dt]);
; DI void attn_phase(const Params& p, const int layer, const int wid_s) {
;     ...
;         asm volatile("s_waitcnt vmcnt(0)" ::: "memory");
;         __syncthreads();
;         RING_ISSUE(0); RING_ISSUE(1);
; #pragma unroll 1
;         for (int si = 0; si < nsteps; ++si) {
;           asm volatile("s_waitcnt vmcnt(1) lgkmcnt(0)" ::: "memory");
;           __builtin_amdgcn_s_barrier();
;           asm volatile("" ::: "memory");
;           RING_ISSUE(si + 2);
;           const int kb = kb0 + si * 32;
;           if (kb > kmax_w || kb < lo_w) continue;
;           if (br == 1 && kb + 31 + 128 <= t0 && __ballot((selmask >> (kb >> 6)) & 1u) == 0ull) continue;
;           LAS unsigned char* slotp = ring + (si % 3) * 8192;
;           KF kv;
; #pragma unroll
;           for (int kt = 0; kt < 2; ++kt)
; #pragma unroll
;             for (int ks = 0; ks < 2; ++ks) kv.k[kt][ks] = *(const LAS half8*)(slotp + kread[kt][ks]);
; #pragma unroll
;           for (int dt = 0; dt < 4; ++dt) kv.v[dt] = *(const LAS half8*)(slotp + vread[dt]);
;           if (br == 1) {
;             const bool bit = (selmask >> (kb >> 6)) & 1u;
;             if (kb + 31 + 128 <= t0) attn_step<true, false>(kv, kb, t, lane, bit, tabh, q, O, nRs, l);
;             else attn_step<true, true>(kv, kb, t, lane, bit, tabh, q, O, nRs, l);
;           } else {
;             const bool gen = (kb + 31 + 128 > t0) || (kb + 512 <= t0 + 15);
.Lat_noga_xc0:
	v_exp_f32_e32 v198, v100
	v_exp_f32_e32 v199, v101
	v_exp_f32_e32 v200, v102
	v_exp_f32_e32 v201, v103
	v_exp_f32_e32 v202, v104
	v_exp_f32_e32 v203, v105
	v_exp_f32_e32 v204, v106
	v_exp_f32_e32 v205, v107
	v_exp_f32_e32 v206, v108
	v_exp_f32_e32 v207, v109
	v_exp_f32_e32 v208, v110
	v_exp_f32_e32 v209, v111
	v_exp_f32_e32 v210, v112
	v_exp_f32_e32 v211, v113
	v_exp_f32_e32 v212, v114
	v_exp_f32_e32 v213, v115
	v_cvt_pkrtz_f16_f32 v120, v198, v199
	v_cvt_pkrtz_f16_f32 v121, v200, v201
	v_cvt_pkrtz_f16_f32 v122, v202, v203
	v_cvt_pkrtz_f16_f32 v123, v204, v205
	v_cvt_pkrtz_f16_f32 v124, v206, v207
	v_cvt_pkrtz_f16_f32 v125, v208, v209
	v_cvt_pkrtz_f16_f32 v126, v210, v211
	v_cvt_pkrtz_f16_f32 v127, v212, v213
	s_waitcnt lgkmcnt(0)
	v_mfma_f32_16x16x32_f16 v[60:63], v[80:83], v[120:123], v[60:63]
	v_add_f32_e32 v214, v214, v198
	v_add_f32_e32 v215, v215, v199
	v_add_f32_e32 v216, v216, v200
	v_add_f32_e32 v217, v217, v201
	v_add_f32_e32 v214, v214, v202
	v_mfma_f32_16x16x32_f16 v[56:59], v[76:79], v[120:123], v[56:59]
	v_add_f32_e32 v215, v215, v203
	v_add_f32_e32 v216, v216, v204
	v_add_f32_e32 v217, v217, v205
	v_add_f32_e32 v218, v218, v206
	v_add_f32_e32 v219, v219, v207
	v_add_f32_e32 v220, v220, v208
	v_mfma_f32_16x16x32_f16 v[52:55], v[72:75], v[120:123], v[52:55]
	v_add_f32_e32 v221, v221, v209
	v_add_f32_e32 v218, v218, v210
	v_add_f32_e32 v219, v219, v211
	v_add_f32_e32 v220, v220, v212
	v_add_f32_e32 v221, v221, v213
	v_mfma_f32_16x16x32_f16 v[48:51], v[68:71], v[120:123], v[48:51]
	s_add_i32 s8, s45, 64
	s_min_i32 s8, s8, s14
	s_mul_i32 s8, s8, s42
	s_mov_b32 s9, 0
	v_lshl_add_u64 v[238:239], v[240:241], 0, s[8:9]
	s_add_i32 m0, s22, 0x1d880
	v_mfma_f32_16x16x32_f16 v[44:47], v[80:83], v[124:127], v[44:47]
	s_nop 0
	global_load_lds_dwordx4 v[238:239], off
	s_add_i32 s45, s45, 32
	s_add_i32 s41, s41, -1
	s_add_i32 s10, s45, 0x9f
	v_mfma_f32_16x16x32_f16 v[40:43], v[76:79], v[124:127], v[40:43]
	s_cmp_gt_i32 s10, s51
	s_cselect_b32 s11, 2, 0
	s_add_i32 s10, s45, 0x1f1
	s_cmp_le_i32 s10, s51
	s_cselect_b32 s10, 2, 0
	s_and_b32 s10, s10, s4
	v_mfma_f32_16x16x32_f16 v[36:39], v[72:75], v[124:127], v[36:39]
	s_or_b32 s11, s11, s10
	s_lshr_b32 s10, s45, 6
	s_bitcmp1_b32 s39, s10
	s_cselect_b32 s10, 1, 0
	s_lshr_b32 s9, s11, 1
	v_mfma_f32_16x16x32_f16 v[32:35], v[68:71], v[124:127], v[32:35]
	s_or_b32 s10, s10, s9
	s_cmp_le_i32 s45, s15
	s_cselect_b32 s10, s10, 0
	s_cmp_ge_i32 s45, s40
	s_cselect_b32 s10, s10, 0
	s_or_b32 s12, s11, s10
	s_mov_b32 s44, 0
	s_cmp_lg_u32 s41, 0
	s_cbranch_scc1 .Lat_xtop1
	s_branch .Lat_xexit
.Lat_xd0:
	s_add_i32 s8, s45, 64
	s_min_i32 s8, s8, s14
	s_mul_i32 s8, s8, s42
	s_mov_b32 s9, 0
	v_lshl_add_u64 v[238:239], v[240:241], 0, s[8:9]
	s_add_i32 m0, s22, 0x1d880
	s_nop 0
	global_load_lds_dwordx4 v[238:239], off
	s_add_i32 s45, s45, 32
	s_add_i32 s41, s41, -1
	s_add_i32 s10, s45, 0x9f
	s_cmp_gt_i32 s10, s51
	s_cselect_b32 s11, 2, 0
	s_add_i32 s10, s45, 0x1f1
	s_cmp_le_i32 s10, s51
	s_cselect_b32 s10, 2, 0
	s_and_b32 s10, s10, s4
	s_or_b32 s11, s11, s10
	s_lshr_b32 s10, s45, 6
	s_bitcmp1_b32 s39, s10
	s_cselect_b32 s10, 1, 0
	s_lshr_b32 s9, s11, 1
	s_or_b32 s10, s10, s9
	s_cmp_le_i32 s45, s15
	s_cselect_b32 s10, s10, 0
	s_cmp_ge_i32 s45, s40
	s_cselect_b32 s10, s10, 0
	s_or_b32 s12, s11, s10
	s_cmp_lg_u32 s41, 0
	s_cbranch_scc1 .Lat_xtop1
	s_branch .Lat_xexit

; template <bool SEL, bool GEN>
; DI void attn_step(const KF& kv, const int kb, const int t, const int lane, const bool selbit,
;                   const LAS float* tabh, const half8 (&q)[2][2], f32x4 (&O)[2][4], const float (&nR)[2], float (&l)[2]) {
;     ...
;   for (int hp = 0; hp < 2; ++hp) {
;     float nm = nR[hp];
;     if (SEL) nm = selbit ? nm : MASKV;
;     const f32x4 c0 = {nm, nm, nm, nm};
; #pragma unroll
;     for (int kt = 0; kt < 2; ++kt) {
;       s[hp][kt] = MFMA16(kv.k[kt][0], q[hp][0], c0);
;       s[hp][kt] = MFMA16(kv.k[kt][1], q[hp][1], s[hp][kt]);
;     }
;   }
;   if (GEN) {
;     const int d0 = t - kb - fq * 4;
; #pragma unroll
;     for (int kt = 0; kt < 2; ++kt)
; #pragma unroll
;       for (int j = 0; j < 4; ++j) {
;         const int dist = d0 - (kt * 16 + j);
;         const bool bad = SEL ? (dist < 0) : ((unsigned)dist >= 512u);
;         const int ix = bad ? 130 : (dist > 128 ? 128 : dist);
; #pragma unroll
;         for (int hp = 0; hp < 2; ++hp) s[hp][kt][j] += tabh[hp * 132 + ix];
;       }
;   }
;   half8 pf[2];
; #pragma unroll
;   for (int hp = 0; hp < 2; ++hp) {
;     f32x4 p0, p1;
; #pragma unroll
;     for (int j = 0; j < 4; ++j) { p0[j] = __builtin_amdgcn_exp2f(s[hp][0][j]); p1[j] = __builtin_amdgcn_exp2f(s[hp][1][j]); }
;     l[hp] += ((p0[0] + p0[1]) + (p0[2] + p0[3])) + ((p1[0] + p1[1]) + (p1[2] + p1[3]));
;     pf[hp] = pack8(p0, p1);
;   }
; #pragma unroll
;   for (int dt = 0; dt < 4; ++dt)
; #pragma unroll
;     for (int hp = 0; hp < 2; ++hp) O[hp][dt] = MFMA16(kv.v[dt], pf[hp], O[hp][dt]);
; DI void attn_phase(const Params& p, const int layer, const int wid_s) {
;     ...
;         asm volatile("s_waitcnt vmcnt(0)" ::: "memory");
;         __syncthreads();
;         RING_ISSUE(0); RING_ISSUE(1);
; #pragma unroll 1
;         for (int si = 0; si < nsteps; ++si) {
;           asm volatile("s_waitcnt vmcnt(1) lgkmcnt(0)" ::: "memory");
;           __builtin_amdgcn_s_barrier();
;           asm volatile("" ::: "memory");
;           RING_ISSUE(si + 2);
;           const int kb = kb0 + si * 32;
;           if (kb > kmax_w || kb < lo_w) continue;
;           if (br == 1 && kb + 31 + 128 <= t0 && __ballot((selmask >> (kb >> 6)) & 1u) == 0ull) continue;
;           LAS unsigned char* slotp = ring + (si % 3) * 8192;
;           KF kv;
; #pragma unroll
;           for (int kt = 0; kt < 2; ++kt)
; #pragma unroll
.Lat_noga_xa1:
	v_exp_f32_e32 v198, v100
	v_exp_f32_e32 v199, v101
	v_exp_f32_e32 v200, v102
	v_exp_f32_e32 v201, v103
	v_exp_f32_e32 v202, v104
	v_exp_f32_e32 v203, v105
	v_exp_f32_e32 v204, v106
	v_exp_f32_e32 v205, v107
	v_exp_f32_e32 v206, v108
	v_exp_f32_e32 v207, v109
	v_exp_f32_e32 v208, v110
	v_exp_f32_e32 v209, v111
	v_exp_f32_e32 v210, v112
	v_exp_f32_e32 v211, v113
	v_exp_f32_e32 v212, v114
	v_exp_f32_e32 v213, v115
	v_cvt_pkrtz_f16_f32 v120, v198, v199
	v_cvt_pkrtz_f16_f32 v121, v200, v201
	v_cvt_pkrtz_f16_f32 v122, v202, v203
	v_cvt_pkrtz_f16_f32 v123, v204, v205
	v_cvt_pkrtz_f16_f32 v124, v206, v207
	v_cvt_pkrtz_f16_f32 v125, v208, v209
	v_cvt_pkrtz_f16_f32 v126, v210, v211
	v_cvt_pkrtz_f16_f32 v127, v212, v213
	s_waitcnt lgkmcnt(0)
	s_and_b32 s44, s12, 2
	s_or_b32 s44, s44, 1
	v_mfma_f32_16x16x32_f16 v[100:103], v[96:99], v[8:11], v[128:131]
	s_add_i32 s8, s45, 64
	s_min_i32 s8, s8, s14
	s_mul_i32 s8, s8, s42
	v_mfma_f32_16x16x32_f16 v[104:107], v[88:91], v[8:11], v[128:131]
	s_mov_b32 s9, 0
	v_lshl_add_u64 v[238:239], v[240:241], 0, s[8:9]
	s_add_i32 m0, s22, 0x20080
	s_nop 0
	v_mfma_f32_16x16x32_f16 v[108:111], v[96:99], v[16:19], v[132:135]
	global_load_lds_dwordx4 v[238:239], off
	s_add_i32 s45, s45, 32
	s_add_i32 s41, s41, -1
	v_mfma_f32_16x16x32_f16 v[112:115], v[88:91], v[16:19], v[132:135]
	s_add_i32 s10, s45, 0x9f
	s_cmp_gt_i32 s10, s51
	s_cselect_b32 s11, 2, 0
	s_add_i32 s10, s45, 0x1f1
	v_mfma_f32_16x16x32_f16 v[100:103], v[92:95], v[12:15], v[100:103]
	s_cmp_le_i32 s10, s51
	s_cselect_b32 s10, 2, 0
	s_and_b32 s10, s10, s4
	v_mfma_f32_16x16x32_f16 v[104:107], v[84:87], v[12:15], v[104:107]
	s_or_b32 s11, s11, s10
	s_lshr_b32 s10, s45, 6
	s_bitcmp1_b32 s39, s10
	s_cselect_b32 s10, 1, 0
	v_mfma_f32_16x16x32_f16 v[108:111], v[92:95], v[20:23], v[108:111]
	s_lshr_b32 s9, s11, 1
	s_or_b32 s10, s10, s9
	s_cmp_le_i32 s45, s15
	v_mfma_f32_16x16x32_f16 v[112:115], v[84:87], v[20:23], v[112:115]
	s_cselect_b32 s10, s10, 0
	s_cmp_ge_i32 s45, s40
	s_cselect_b32 s10, s10, 0
	s_or_b32 s12, s11, s10
	v_mfma_f32_16x16x32_f16 v[60:63], v[80:83], v[120:123], v[60:63]
	v_add_f32_e32 v214, v214, v198
	v_add_f32_e32 v215, v215, v199
	v_mfma_f32_16x16x32_f16 v[56:59], v[76:79], v[120:123], v[56:59]
	v_add_f32_e32 v216, v216, v200
	v_add_f32_e32 v217, v217, v201
	v_mfma_f32_16x16x32_f16 v[52:55], v[72:75], v[120:123], v[52:55]
	v_add_f32_e32 v214, v214, v202
	v_add_f32_e32 v215, v215, v203
	v_mfma_f32_16x16x32_f16 v[48:51], v[68:71], v[120:123], v[48:51]
	v_add_f32_e32 v216, v216, v204
	v_add_f32_e32 v217, v217, v205
	v_mfma_f32_16x16x32_f16 v[44:47], v[80:83], v[124:127], v[44:47]
	v_add_f32_e32 v218, v218, v206
	v_add_f32_e32 v219, v219, v207
	v_mfma_f32_16x16x32_f16 v[40:43], v[76:79], v[124:127], v[40:43]
	v_add_f32_e32 v220, v220, v208
	v_add_f32_e32 v221, v221, v209
	v_mfma_f32_16x16x32_f16 v[36:39], v[72:75], v[124:127], v[36:39]
	v_add_f32_e32 v218, v218, v210
	v_add_f32_e32 v219, v219, v211
	v_mfma_f32_16x16x32_f16 v[32:35], v[68:71], v[124:127], v[32:35]
	v_add_f32_e32 v220, v220, v212
	v_add_f32_e32 v221, v221, v213
	ds_read_b128 v[80:83], v65 offset:12288
	ds_read_b128 v[76:79], v65 offset:13312
	ds_read_b128 v[72:75], v65 offset:14336
	ds_read_b128 v[68:71], v65 offset:15360
	s_cmp_lg_u32 s41, 0
	s_cbranch_scc1 .Lat_xtop2
	s_branch .Lat_xexit
.Lat_xb1:
	s_waitcnt lgkmcnt(0)
	s_and_b32 s44, s12, 2
	s_or_b32 s44, s44, 1
	v_mfma_f32_16x16x32_f16 v[100:103], v[96:99], v[8:11], v[128:131]
	s_add_i32 s8, s45, 64
	s_min_i32 s8, s8, s14
	s_mul_i32 s8, s8, s42
	v_mfma_f32_16x16x32_f16 v[104:107], v[88:91], v[8:11], v[128:131]
	s_mov_b32 s9, 0
	v_lshl_add_u64 v[238:239], v[240:241], 0, s[8:9]
	s_add_i32 m0, s22, 0x20080
	s_nop 0
	v_mfma_f32_16x16x32_f16 v[108:111], v[96:99], v[16:19], v[132:135]
	global_load_lds_dwordx4 v[238:239], off
	s_add_i32 s45, s45, 32
	s_add_i32 s41, s41, -1
	v_mfma_f32_16x16x32_f16 v[112:115], v[88:91], v[16:19], v[132:135]
	s_add_i32 s10, s45, 0x9f
	s_cmp_gt_i32 s10, s51
	s_cselect_b32 s11, 2, 0
	s_add_i32 s10, s45, 0x1f1
	v_mfma_f32_16x16x32_f16 v[100:103], v[92:95], v[12:15], v[100:103]
	s_cmp_le_i32 s10, s51
	s_cselect_b32 s10, 2, 0
	s_and_b32 s10, s10, s4
	v_mfma_f32_16x16x32_f16 v[104:107], v[84:87], v[12:15], v[104:107]
	s_or_b32 s11, s11, s10
	s_lshr_b32 s10, s45, 6
	s_bitcmp1_b32 s39, s10
	s_cselect_b32 s10, 1, 0
	v_mfma_f32_16x16x32_f16 v[108:111], v[92:95], v[20:23], v[108:111]
	s_lshr_b32 s9, s11, 1
	s_or_b32 s10, s10, s9
	s_cmp_le_i32 s45, s15
	v_mfma_f32_16x16x32_f16 v[112:115], v[84:87], v[20:23], v[112:115]
	s_cselect_b32 s10, s10, 0
	s_cmp_ge_i32 s45, s40
	s_cselect_b32 s10, s10, 0
	s_or_b32 s12, s11, s10
	ds_read_b128 v[80:83], v65 offset:12288
	ds_read_b128 v[76:79], v65 offset:13312
	ds_read_b128 v[72:75], v65 offset:14336
	ds_read_b128 v[68:71], v65 offset:15360
	s_cmp_lg_u32 s41, 0
	s_cbranch_scc1 .Lat_xtop2
	s_branch .Lat_xexit

; #define MFMA16(a, b, c) __builtin_amdgcn_mfma_f32_16x16x32_f16((a), (b), (c), 0, 0, 0)
; #define LAS __attribute__((address_space(3)))
; template <bool SEL, bool GEN>
; DI void attn_step(const KF& kv, const int kb, const int t, const int lane, const bool selbit,
;                   const LAS float* tabh, const half8 (&q)[2][2], f32x4 (&O)[2][4], const float (&nR)[2], float (&l)[2]) {
;     ...
;     for (int j = 0; j < 4; ++j) { p0[j] = __builtin_amdgcn_exp2f(s[hp][0][j]); p1[j] = __builtin_amdgcn_exp2f(s[hp][1][j]); }
;     l[hp] += ((p0[0] + p0[1]) + (p0[2] + p0[3])) + ((p1[0] + p1[1]) + (p1[2] + p1[3]));
;     pf[hp] = pack8(p0, p1);
;   }
; #pragma unroll
;   for (int dt = 0; dt < 4; ++dt)
; #pragma unroll
;     for (int hp = 0; hp < 2; ++hp) O[hp][dt] = MFMA16(kv.v[dt], pf[hp], O[hp][dt]);
; DI void attn_phase(const Params& p, const int layer, const int wid_s) {
;     ...
;         asm volatile("s_waitcnt vmcnt(0)" ::: "memory");
;         __syncthreads();
;         RING_ISSUE(0); RING_ISSUE(1);
; #pragma unroll 1
;         for (int si = 0; si < nsteps; ++si) {
;           asm volatile("s_waitcnt vmcnt(1) lgkmcnt(0)" ::: "memory");
;           __builtin_amdgcn_s_barrier();
;           asm volatile("" ::: "memory");
;           RING_ISSUE(si + 2);
;           const int kb = kb0 + si * 32;
;           if (kb > kmax_w || kb < lo_w) continue;
;           if (br == 1 && kb + 31 + 128 <= t0 && __ballot((selmask >> (kb >> 6)) & 1u) == 0ull) continue;
;           LAS unsigned char* slotp = ring + (si % 3) * 8192;
;           KF kv;
; #pragma unroll
;           for (int kt = 0; kt < 2; ++kt)
; #pragma unroll
;             for (int ks = 0; ks < 2; ++ks) kv.k[kt][ks] = *(const LAS half8*)(slotp + kread[kt][ks]);
; #pragma unroll
;           for (int dt = 0; dt < 4; ++dt) kv.v[dt] = *(const LAS half8*)(slotp + vread[dt]);
;           if (br == 1) {
;             const bool bit = (selmask >> (kb >> 6)) & 1u;
;             if (kb + 31 + 128 <= t0) attn_step<true, false>(kv, kb, t, lane, bit, tabh, q, O, nRs, l);
;             else attn_step<true, true>(kv, kb, t, lane, bit, tabh, q, O, nRs, l);
;           } else {
;             const bool gen = (kb + 31 + 128 > t0) || (kb + 512 <= t0 + 15);
.Lat_noga_xc1:
	v_exp_f32_e32 v198, v100
	v_exp_f32_e32 v199, v101
	v_exp_f32_e32 v200, v102
	v_exp_f32_e32 v201, v103
	v_exp_f32_e32 v202, v104
	v_exp_f32_e32 v203, v105
	v_exp_f32_e32 v204, v106
	v_exp_f32_e32 v205, v107
	v_exp_f32_e32 v206, v108
	v_exp_f32_e32 v207, v109
	v_exp_f32_e32 v208, v110
	v_exp_f32_e32 v209, v111
	v_exp_f32_e32 v210, v112
	v_exp_f32_e32 v211, v113
	v_exp_f32_e32 v212, v114
	v_exp_f32_e32 v213, v115
	v_cvt_pkrtz_f16_f32 v120, v198, v199
	v_cvt_pkrtz_f16_f32 v121, v200, v201
	v_cvt_pkrtz_f16_f32 v122, v202, v203
	v_cvt_pkrtz_f16_f32 v123, v204, v205
	v_cvt_pkrtz_f16_f32 v124, v206, v207
	v_cvt_pkrtz_f16_f32 v125, v208, v209
	v_cvt_pkrtz_f16_f32 v126, v210, v211
	v_cvt_pkrtz_f16_f32 v127, v212, v213
	s_waitcnt lgkmcnt(0)
	v_mfma_f32_16x16x32_f16 v[60:63], v[80:83], v[120:123], v[60:63]
	v_add_f32_e32 v214, v214, v198
	v_add_f32_e32 v215, v215, v199
	v_add_f32_e32 v216, v216, v200
	v_add_f32_e32 v217, v217, v201
	v_add_f32_e32 v214, v214, v202
	v_mfma_f32_16x16x32_f16 v[56:59], v[76:79], v[120:123], v[56:59]
	v_add_f32_e32 v215, v215, v203
	v_add_f32_e32 v216, v216, v204
	v_add_f32_e32 v217, v217, v205
	v_add_f32_e32 v218, v218, v206
	v_add_f32_e32 v219, v219, v207
	v_add_f32_e32 v220, v220, v208
	v_mfma_f32_16x16x32_f16 v[52:55], v[72:75], v[120:123], v[52:55]
	v_add_f32_e32 v221, v221, v209
	v_add_f32_e32 v218, v218, v210
	v_add_f32_e32 v219, v219, v211
	v_add_f32_e32 v220, v220, v212
	v_add_f32_e32 v221, v221, v213
	v_mfma_f32_16x16x32_f16 v[48:51], v[68:71], v[120:123], v[48:51]
	s_add_i32 s8, s45, 64
	s_min_i32 s8, s8, s14
	s_mul_i32 s8, s8, s42
	s_mov_b32 s9, 0
	v_lshl_add_u64 v[238:239], v[240:241], 0, s[8:9]
	s_add_i32 m0, s22, 0x20080
	v_mfma_f32_16x16x32_f16 v[44:47], v[80:83], v[124:127], v[44:47]
	s_nop 0
	global_load_lds_dwordx4 v[238:239], off
	s_add_i32 s45, s45, 32
	s_add_i32 s41, s41, -1
	s_add_i32 s10, s45, 0x9f
	v_mfma_f32_16x16x32_f16 v[40:43], v[76:79], v[124:127], v[40:43]
	s_cmp_gt_i32 s10, s51
	s_cselect_b32 s11, 2, 0
	s_add_i32 s10, s45, 0x1f1
	s_cmp_le_i32 s10, s51
	s_cselect_b32 s10, 2, 0
	s_and_b32 s10, s10, s4
	v_mfma_f32_16x16x32_f16 v[36:39], v[72:75], v[124:127], v[36:39]
	s_or_b32 s11, s11, s10
	s_lshr_b32 s10, s45, 6
	s_bitcmp1_b32 s39, s10
	s_cselect_b32 s10, 1, 0
	s_lshr_b32 s9, s11, 1
	v_mfma_f32_16x16x32_f16 v[32:35], v[68:71], v[124:127], v[32:35]
	s_or_b32 s10, s10, s9
	s_cmp_le_i32 s45, s15
	s_cselect_b32 s10, s10, 0
	s_cmp_ge_i32 s45, s40
	s_cselect_b32 s10, s10, 0
	s_or_b32 s12, s11, s10
	s_mov_b32 s44, 0
	s_cmp_lg_u32 s41, 0
	s_cbranch_scc1 .Lat_xtop2
	s_branch .Lat_xexit
.Lat_xd1:
	s_add_i32 s8, s45, 64
	s_min_i32 s8, s8, s14
	s_mul_i32 s8, s8, s42
	s_mov_b32 s9, 0
	v_lshl_add_u64 v[238:239], v[240:241], 0, s[8:9]
	s_add_i32 m0, s22, 0x20080
	s_nop 0
	global_load_lds_dwordx4 v[238:239], off
	s_add_i32 s45, s45, 32
	s_add_i32 s41, s41, -1
	s_add_i32 s10, s45, 0x9f
	s_cmp_gt_i32 s10, s51
	s_cselect_b32 s11, 2, 0
	s_add_i32 s10, s45, 0x1f1
	s_cmp_le_i32 s10, s51
	s_cselect_b32 s10, 2, 0
	s_and_b32 s10, s10, s4
	s_or_b32 s11, s11, s10
	s_lshr_b32 s10, s45, 6
	s_bitcmp1_b32 s39, s10
	s_cselect_b32 s10, 1, 0
	s_lshr_b32 s9, s11, 1
	s_or_b32 s10, s10, s9
	s_cmp_le_i32 s45, s15
	s_cselect_b32 s10, s10, 0
	s_cmp_ge_i32 s45, s40
	s_cselect_b32 s10, s10, 0
	s_or_b32 s12, s11, s10
	s_cmp_lg_u32 s41, 0
	s_cbranch_scc1 .Lat_xtop2
	s_branch .Lat_xexit

; template <bool SEL, bool GEN>
; DI void attn_step(const KF& kv, const int kb, const int t, const int lane, const bool selbit,
;                   const LAS float* tabh, const half8 (&q)[2][2], f32x4 (&O)[2][4], const float (&nR)[2], float (&l)[2]) {
;     ...
;   for (int hp = 0; hp < 2; ++hp) {
;     float nm = nR[hp];
;     if (SEL) nm = selbit ? nm : MASKV;
;     const f32x4 c0 = {nm, nm, nm, nm};
; #pragma unroll
;     for (int kt = 0; kt < 2; ++kt) {
;       s[hp][kt] = MFMA16(kv.k[kt][0], q[hp][0], c0);
;       s[hp][kt] = MFMA16(kv.k[kt][1], q[hp][1], s[hp][kt]);
;     }
;   }
;   if (GEN) {
;     const int d0 = t - kb - fq * 4;
; #pragma unroll
;     for (int kt = 0; kt < 2; ++kt)
; #pragma unroll
;       for (int j = 0; j < 4; ++j) {
;         const int dist = d0 - (kt * 16 + j);
;         const bool bad = SEL ? (dist < 0) : ((unsigned)dist >= 512u);
;         const int ix = bad ? 130 : (dist > 128 ? 128 : dist);
; #pragma unroll
;         for (int hp = 0; hp < 2; ++hp) s[hp][kt][j] += tabh[hp * 132 + ix];
;       }
;   }
;   half8 pf[2];
; #pragma unroll
;   for (int hp = 0; hp < 2; ++hp) {
;     f32x4 p0, p1;
; #pragma unroll
;     for (int j = 0; j < 4; ++j) { p0[j] = __builtin_amdgcn_exp2f(s[hp][0][j]); p1[j] = __builtin_amdgcn_exp2f(s[hp][1][j]); }
;     l[hp] += ((p0[0] + p0[1]) + (p0[2] + p0[3])) + ((p1[0] + p1[1]) + (p1[2] + p1[3]));
;     pf[hp] = pack8(p0, p1);
;   }
; #pragma unroll
;   for (int dt = 0; dt < 4; ++dt)
; #pragma unroll
;     for (int hp = 0; hp < 2; ++hp) O[hp][dt] = MFMA16(kv.v[dt], pf[hp], O[hp][dt]);
; DI void attn_phase(const Params& p, const int layer, const int wid_s) {
;     ...
;         asm volatile("s_waitcnt vmcnt(0)" ::: "memory");
;         __syncthreads();
;         RING_ISSUE(0); RING_ISSUE(1);
; #pragma unroll 1
;         for (int si = 0; si < nsteps; ++si) {
;           asm volatile("s_waitcnt vmcnt(1) lgkmcnt(0)" ::: "memory");
;           __builtin_amdgcn_s_barrier();
;           asm volatile("" ::: "memory");
;           RING_ISSUE(si + 2);
;           const int kb = kb0 + si * 32;
;           if (kb > kmax_w || kb < lo_w) continue;
;           if (br == 1 && kb + 31 + 128 <= t0 && __ballot((selmask >> (kb >> 6)) & 1u) == 0ull) continue;
;           LAS unsigned char* slotp = ring + (si % 3) * 8192;
;           KF kv;
; #pragma unroll
;           for (int kt = 0; kt < 2; ++kt)
; #pragma unroll
.Lat_noga_xa2:
	v_exp_f32_e32 v198, v100
	v_exp_f32_e32 v199, v101
	v_exp_f32_e32 v200, v102
	v_exp_f32_e32 v201, v103
	v_exp_f32_e32 v202, v104
	v_exp_f32_e32 v203, v105
	v_exp_f32_e32 v204, v106
	v_exp_f32_e32 v205, v107
	v_exp_f32_e32 v206, v108
	v_exp_f32_e32 v207, v109
	v_exp_f32_e32 v208, v110
	v_exp_f32_e32 v209, v111
	v_exp_f32_e32 v210, v112
	v_exp_f32_e32 v211, v113
	v_exp_f32_e32 v212, v114
	v_exp_f32_e32 v213, v115
	v_cvt_pkrtz_f16_f32 v120, v198, v199
	v_cvt_pkrtz_f16_f32 v121, v200, v201
	v_cvt_pkrtz_f16_f32 v122, v202, v203
	v_cvt_pkrtz_f16_f32 v123, v204, v205
	v_cvt_pkrtz_f16_f32 v124, v206, v207
	v_cvt_pkrtz_f16_f32 v125, v208, v209
	v_cvt_pkrtz_f16_f32 v126, v210, v211
	v_cvt_pkrtz_f16_f32 v127, v212, v213
	s_waitcnt lgkmcnt(0)
	s_and_b32 s44, s12, 2
	s_or_b32 s44, s44, 1
	v_mfma_f32_16x16x32_f16 v[100:103], v[96:99], v[8:11], v[128:131]
	s_add_i32 s8, s45, 64
	s_min_i32 s8, s8, s14
	s_mul_i32 s8, s8, s42
	v_mfma_f32_16x16x32_f16 v[104:107], v[88:91], v[8:11], v[128:131]
	s_mov_b32 s9, 0
	v_lshl_add_u64 v[238:239], v[240:241], 0, s[8:9]
	s_add_i32 m0, s22, 0x19880
	s_nop 0
	v_mfma_f32_16x16x32_f16 v[108:111], v[96:99], v[16:19], v[132:135]
	global_load_lds_dwordx4 v[238:239], off
	s_add_i32 s45, s45, 32
	s_add_i32 s41, s41, -1
	v_mfma_f32_16x16x32_f16 v[112:115], v[88:91], v[16:19], v[132:135]
	s_add_i32 s10, s45, 0x9f
	s_cmp_gt_i32 s10, s51
	s_cselect_b32 s11, 2, 0
	s_add_i32 s10, s45, 0x1f1
	v_mfma_f32_16x16x32_f16 v[100:103], v[92:95], v[12:15], v[100:103]
	s_cmp_le_i32 s10, s51
	s_cselect_b32 s10, 2, 0
	s_and_b32 s10, s10, s4
	v_mfma_f32_16x16x32_f16 v[104:107], v[84:87], v[12:15], v[104:107]
	s_or_b32 s11, s11, s10
	s_lshr_b32 s10, s45, 6
	s_bitcmp1_b32 s39, s10
	s_cselect_b32 s10, 1, 0
	v_mfma_f32_16x16x32_f16 v[108:111], v[92:95], v[20:23], v[108:111]
	s_lshr_b32 s9, s11, 1
	s_or_b32 s10, s10, s9
	s_cmp_le_i32 s45, s15
	v_mfma_f32_16x16x32_f16 v[112:115], v[84:87], v[20:23], v[112:115]
	s_cselect_b32 s10, s10, 0
	s_cmp_ge_i32 s45, s40
	s_cselect_b32 s10, s10, 0
	s_or_b32 s12, s11, s10
	v_mfma_f32_16x16x32_f16 v[60:63], v[80:83], v[120:123], v[60:63]
	v_add_f32_e32 v214, v214, v198
	v_add_f32_e32 v215, v215, v199
	v_mfma_f32_16x16x32_f16 v[56:59], v[76:79], v[120:123], v[56:59]
	v_add_f32_e32 v216, v216, v200
	v_add_f32_e32 v217, v217, v201
	v_mfma_f32_16x16x32_f16 v[52:55], v[72:75], v[120:123], v[52:55]
	v_add_f32_e32 v214, v214, v202
	v_add_f32_e32 v215, v215, v203
	v_mfma_f32_16x16x32_f16 v[48:51], v[68:71], v[120:123], v[48:51]
	v_add_f32_e32 v216, v216, v204
	v_add_f32_e32 v217, v217, v205
	v_mfma_f32_16x16x32_f16 v[44:47], v[80:83], v[124:127], v[44:47]
	v_add_f32_e32 v218, v218, v206
	v_add_f32_e32 v219, v219, v207
	v_mfma_f32_16x16x32_f16 v[40:43], v[76:79], v[124:127], v[40:43]
	v_add_f32_e32 v220, v220, v208
	v_add_f32_e32 v221, v221, v209
	v_mfma_f32_16x16x32_f16 v[36:39], v[72:75], v[124:127], v[36:39]
	v_add_f32_e32 v218, v218, v210
	v_add_f32_e32 v219, v219, v211
	v_mfma_f32_16x16x32_f16 v[32:35], v[68:71], v[124:127], v[32:35]
	v_add_f32_e32 v220, v220, v212
	v_add_f32_e32 v221, v221, v213
	ds_read_b128 v[80:83], v65 offset:20480
	ds_read_b128 v[76:79], v65 offset:21504
	ds_read_b128 v[72:75], v65 offset:22528
	ds_read_b128 v[68:71], v65 offset:23552
	s_cmp_lg_u32 s41, 0
	s_cbranch_scc1 .Lat_xtop3
	s_branch .Lat_xexit
.Lat_xb2:
	s_waitcnt lgkmcnt(0)
	s_and_b32 s44, s12, 2
	s_or_b32 s44, s44, 1
	v_mfma_f32_16x16x32_f16 v[100:103], v[96:99], v[8:11], v[128:131]
	s_add_i32 s8, s45, 64
	s_min_i32 s8, s8, s14
	s_mul_i32 s8, s8, s42
	v_mfma_f32_16x16x32_f16 v[104:107], v[88:91], v[8:11], v[128:131]
	s_mov_b32 s9, 0
	v_lshl_add_u64 v[238:239], v[240:241], 0, s[8:9]
	s_add_i32 m0, s22, 0x19880
	s_nop 0
	v_mfma_f32_16x16x32_f16 v[108:111], v[96:99], v[16:19], v[132:135]
	global_load_lds_dwordx4 v[238:239], off
	s_add_i32 s45, s45, 32
	s_add_i32 s41, s41, -1
	v_mfma_f32_16x16x32_f16 v[112:115], v[88:91], v[16:19], v[132:135]
	s_add_i32 s10, s45, 0x9f
	s_cmp_gt_i32 s10, s51
	s_cselect_b32 s11, 2, 0
	s_add_i32 s10, s45, 0x1f1
	v_mfma_f32_16x16x32_f16 v[100:103], v[92:95], v[12:15], v[100:103]
	s_cmp_le_i32 s10, s51
	s_cselect_b32 s10, 2, 0
	s_and_b32 s10, s10, s4
	v_mfma_f32_16x16x32_f16 v[104:107], v[84:87], v[12:15], v[104:107]
	s_or_b32 s11, s11, s10
	s_lshr_b32 s10, s45, 6
	s_bitcmp1_b32 s39, s10
	s_cselect_b32 s10, 1, 0
	v_mfma_f32_16x16x32_f16 v[108:111], v[92:95], v[20:23], v[108:111]
	s_lshr_b32 s9, s11, 1
	s_or_b32 s10, s10, s9
	s_cmp_le_i32 s45, s15
	v_mfma_f32_16x16x32_f16 v[112:115], v[84:87], v[20:23], v[112:115]
	s_cselect_b32 s10, s10, 0
	s_cmp_ge_i32 s45, s40
	s_cselect_b32 s10, s10, 0
	s_or_b32 s12, s11, s10
	ds_read_b128 v[80:83], v65 offset:20480
	ds_read_b128 v[76:79], v65 offset:21504
	ds_read_b128 v[72:75], v65 offset:22528
	ds_read_b128 v[68:71], v65 offset:23552
	s_cmp_lg_u32 s41, 0
	s_cbranch_scc1 .Lat_xtop3
	s_branch .Lat_xexit

; #define MFMA16(a, b, c) __builtin_amdgcn_mfma_f32_16x16x32_f16((a), (b), (c), 0, 0, 0)
; #define LAS __attribute__((address_space(3)))
; template <bool SEL, bool GEN>
; DI void attn_step(const KF& kv, const int kb, const int t, const int lane, const bool selbit,
;                   const LAS float* tabh, const half8 (&q)[2][2], f32x4 (&O)[2][4], const float (&nR)[2], float (&l)[2]) {
;     ...
;     for (int j = 0; j < 4; ++j) { p0[j] = __builtin_amdgcn_exp2f(s[hp][0][j]); p1[j] = __builtin_amdgcn_exp2f(s[hp][1][j]); }
;     l[hp] += ((p0[0] + p0[1]) + (p0[2] + p0[3])) + ((p1[0] + p1[1]) + (p1[2] + p1[3]));
;     pf[hp] = pack8(p0, p1);
;   }
; #pragma unroll
;   for (int dt = 0; dt < 4; ++dt)
; #pragma unroll
;     for (int hp = 0; hp < 2; ++hp) O[hp][dt] = MFMA16(kv.v[dt], pf[hp], O[hp][dt]);
; DI void attn_phase(const Params& p, const int layer, const int wid_s) {
;     ...
;         asm volatile("s_waitcnt vmcnt(0)" ::: "memory");
;         __syncthreads();
;         RING_ISSUE(0); RING_ISSUE(1);
; #pragma unroll 1
;         for (int si = 0; si < nsteps; ++si) {
;           asm volatile("s_waitcnt vmcnt(1) lgkmcnt(0)" ::: "memory");
;           __builtin_amdgcn_s_barrier();
;           asm volatile("" ::: "memory");
;           RING_ISSUE(si + 2);
;           const int kb = kb0 + si * 32;
;           if (kb > kmax_w || kb < lo_w) continue;
;           if (br == 1 && kb + 31 + 128 <= t0 && __ballot((selmask >> (kb >> 6)) & 1u) == 0ull) continue;
;           LAS unsigned char* slotp = ring + (si % 3) * 8192;
;           KF kv;
; #pragma unroll
;           for (int kt = 0; kt < 2; ++kt)
; #pragma unroll
;             for (int ks = 0; ks < 2; ++ks) kv.k[kt][ks] = *(const LAS half8*)(slotp + kread[kt][ks]);
; #pragma unroll
;           for (int dt = 0; dt < 4; ++dt) kv.v[dt] = *(const LAS half8*)(slotp + vread[dt]);
;           if (br == 1) {
;             const bool bit = (selmask >> (kb >> 6)) & 1u;
;             if (kb + 31 + 128 <= t0) attn_step<true, false>(kv, kb, t, lane, bit, tabh, q, O, nRs, l);
;             else attn_step<true, true>(kv, kb, t, lane, bit, tabh, q, O, nRs, l);
;           } else {
;             const bool gen = (kb + 31 + 128 > t0) || (kb + 512 <= t0 + 15);
.Lat_noga_xc2:
	v_exp_f32_e32 v198, v100
	v_exp_f32_e32 v199, v101
	v_exp_f32_e32 v200, v102
	v_exp_f32_e32 v201, v103
	v_exp_f32_e32 v202, v104
	v_exp_f32_e32 v203, v105
	v_exp_f32_e32 v204, v106
	v_exp_f32_e32 v205, v107
	v_exp_f32_e32 v206, v108
	v_exp_f32_e32 v207, v109
	v_exp_f32_e32 v208, v110
	v_exp_f32_e32 v209, v111
	v_exp_f32_e32 v210, v112
	v_exp_f32_e32 v211, v113
	v_exp_f32_e32 v212, v114
	v_exp_f32_e32 v213, v115
	v_cvt_pkrtz_f16_f32 v120, v198, v199
	v_cvt_pkrtz_f16_f32 v121, v200, v201
	v_cvt_pkrtz_f16_f32 v122, v202, v203
	v_cvt_pkrtz_f16_f32 v123, v204, v205
	v_cvt_pkrtz_f16_f32 v124, v206, v207
	v_cvt_pkrtz_f16_f32 v125, v208, v209
	v_cvt_pkrtz_f16_f32 v126, v210, v211
	v_cvt_pkrtz_f16_f32 v127, v212, v213
	s_waitcnt lgkmcnt(0)
	v_mfma_f32_16x16x32_f16 v[60:63], v[80:83], v[120:123], v[60:63]
	v_add_f32_e32 v214, v214, v198
	v_add_f32_e32 v215, v215, v199
	v_add_f32_e32 v216, v216, v200
	v_add_f32_e32 v217, v217, v201
	v_add_f32_e32 v214, v214, v202
	v_mfma_f32_16x16x32_f16 v[56:59], v[76:79], v[120:123], v[56:59]
	v_add_f32_e32 v215, v215, v203
	v_add_f32_e32 v216, v216, v204
	v_add_f32_e32 v217, v217, v205
	v_add_f32_e32 v218, v218, v206
	v_add_f32_e32 v219, v219, v207
	v_add_f32_e32 v220, v220, v208
	v_mfma_f32_16x16x32_f16 v[52:55], v[72:75], v[120:123], v[52:55]
	v_add_f32_e32 v221, v221, v209
	v_add_f32_e32 v218, v218, v210
	v_add_f32_e32 v219, v219, v211
	v_add_f32_e32 v220, v220, v212
	v_add_f32_e32 v221, v221, v213
	v_mfma_f32_16x16x32_f16 v[48:51], v[68:71], v[120:123], v[48:51]
	s_add_i32 s8, s45, 64
	s_min_i32 s8, s8, s14
	s_mul_i32 s8, s8, s42
	s_mov_b32 s9, 0
	v_lshl_add_u64 v[238:239], v[240:241], 0, s[8:9]
	s_add_i32 m0, s22, 0x19880
	v_mfma_f32_16x16x32_f16 v[44:47], v[80:83], v[124:127], v[44:47]
	s_nop 0
	global_load_lds_dwordx4 v[238:239], off
	s_add_i32 s45, s45, 32
	s_add_i32 s41, s41, -1
	s_add_i32 s10, s45, 0x9f
	v_mfma_f32_16x16x32_f16 v[40:43], v[76:79], v[124:127], v[40:43]
	s_cmp_gt_i32 s10, s51
	s_cselect_b32 s11, 2, 0
	s_add_i32 s10, s45, 0x1f1
	s_cmp_le_i32 s10, s51
	s_cselect_b32 s10, 2, 0
	s_and_b32 s10, s10, s4
	v_mfma_f32_16x16x32_f16 v[36:39], v[72:75], v[124:127], v[36:39]
	s_or_b32 s11, s11, s10
	s_lshr_b32 s10, s45, 6
	s_bitcmp1_b32 s39, s10
	s_cselect_b32 s10, 1, 0
	s_lshr_b32 s9, s11, 1
	v_mfma_f32_16x16x32_f16 v[32:35], v[68:71], v[124:127], v[32:35]
	s_or_b32 s10, s10, s9
	s_cmp_le_i32 s45, s15
	s_cselect_b32 s10, s10, 0
	s_cmp_ge_i32 s45, s40
	s_cselect_b32 s10, s10, 0
	s_or_b32 s12, s11, s10
	s_mov_b32 s44, 0
	s_cmp_lg_u32 s41, 0
	s_cbranch_scc1 .Lat_xtop3
	s_branch .Lat_xexit
.Lat_xd2:
	s_add_i32 s8, s45, 64
	s_min_i32 s8, s8, s14
	s_mul_i32 s8, s8, s42
	s_mov_b32 s9, 0
	v_lshl_add_u64 v[238:239], v[240:241], 0, s[8:9]
	s_add_i32 m0, s22, 0x19880
	s_nop 0
	global_load_lds_dwordx4 v[238:239], off
	s_add_i32 s45, s45, 32
	s_add_i32 s41, s41, -1
	s_add_i32 s10, s45, 0x9f
	s_cmp_gt_i32 s10, s51
	s_cselect_b32 s11, 2, 0
	s_add_i32 s10, s45, 0x1f1
	s_cmp_le_i32 s10, s51
	s_cselect_b32 s10, 2, 0
	s_and_b32 s10, s10, s4
	s_or_b32 s11, s11, s10
	s_lshr_b32 s10, s45, 6
	s_bitcmp1_b32 s39, s10
	s_cselect_b32 s10, 1, 0
	s_lshr_b32 s9, s11, 1
	s_or_b32 s10, s10, s9
	s_cmp_le_i32 s45, s15
	s_cselect_b32 s10, s10, 0
	s_cmp_ge_i32 s45, s40
	s_cselect_b32 s10, s10, 0
	s_or_b32 s12, s11, s10
	s_cmp_lg_u32 s41, 0
	s_cbranch_scc1 .Lat_xtop3
	s_branch .Lat_xexit

; template <bool SEL, bool GEN>
; DI void attn_step(const KF& kv, const int kb, const int t, const int lane, const bool selbit,
;                   const LAS float* tabh, const half8 (&q)[2][2], f32x4 (&O)[2][4], const float (&nR)[2], float (&l)[2]) {
;     ...
;   for (int hp = 0; hp < 2; ++hp) {
;     float nm = nR[hp];
;     if (SEL) nm = selbit ? nm : MASKV;
;     const f32x4 c0 = {nm, nm, nm, nm};
; #pragma unroll
;     for (int kt = 0; kt < 2; ++kt) {
;       s[hp][kt] = MFMA16(kv.k[kt][0], q[hp][0], c0);
;       s[hp][kt] = MFMA16(kv.k[kt][1], q[hp][1], s[hp][kt]);
;     }
;   }
;   if (GEN) {
;     const int d0 = t - kb - fq * 4;
; #pragma unroll
;     for (int kt = 0; kt < 2; ++kt)
; #pragma unroll
;       for (int j = 0; j < 4; ++j) {
;         const int dist = d0 - (kt * 16 + j);
;         const bool bad = SEL ? (dist < 0) : ((unsigned)dist >= 512u);
;         const int ix = bad ? 130 : (dist > 128 ? 128 : dist);
; #pragma unroll
;         for (int hp = 0; hp < 2; ++hp) s[hp][kt][j] += tabh[hp * 132 + ix];
;       }
;   }
;   half8 pf[2];
; #pragma unroll
;   for (int hp = 0; hp < 2; ++hp) {
;     f32x4 p0, p1;
; #pragma unroll
;     for (int j = 0; j < 4; ++j) { p0[j] = __builtin_amdgcn_exp2f(s[hp][0][j]); p1[j] = __builtin_amdgcn_exp2f(s[hp][1][j]); }
;     l[hp] += ((p0[0] + p0[1]) + (p0[2] + p0[3])) + ((p1[0] + p1[1]) + (p1[2] + p1[3]));
;     pf[hp] = pack8(p0, p1);
;   }
; #pragma unroll
;   for (int dt = 0; dt < 4; ++dt)
; #pragma unroll
;     for (int hp = 0; hp < 2; ++hp) O[hp][dt] = MFMA16(kv.v[dt], pf[hp], O[hp][dt]);
; DI void attn_phase(const Params& p, const int layer, const int wid_s) {
;     ...
;         asm volatile("s_waitcnt vmcnt(0)" ::: "memory");
;         __syncthreads();
;         RING_ISSUE(0); RING_ISSUE(1);
; #pragma unroll 1
;         for (int si = 0; si < nsteps; ++si) {
;           asm volatile("s_waitcnt vmcnt(1) lgkmcnt(0)" ::: "memory");
;           __builtin_amdgcn_s_barrier();
;           asm volatile("" ::: "memory");
;           RING_ISSUE(si + 2);
;           const int kb = kb0 + si * 32;
;           if (kb > kmax_w || kb < lo_w) continue;
;           if (br == 1 && kb + 31 + 128 <= t0 && __ballot((selmask >> (kb >> 6)) & 1u) == 0ull) continue;
;           LAS unsigned char* slotp = ring + (si % 3) * 8192;
;           KF kv;
; #pragma unroll
;           for (int kt = 0; kt < 2; ++kt)
; #pragma unroll
.Lat_noga_xa3:
	v_exp_f32_e32 v198, v100
	v_exp_f32_e32 v199, v101
	v_exp_f32_e32 v200, v102
	v_exp_f32_e32 v201, v103
	v_exp_f32_e32 v202, v104
	v_exp_f32_e32 v203, v105
	v_exp_f32_e32 v204, v106
	v_exp_f32_e32 v205, v107
	v_exp_f32_e32 v206, v108
	v_exp_f32_e32 v207, v109
	v_exp_f32_e32 v208, v110
	v_exp_f32_e32 v209, v111
	v_exp_f32_e32 v210, v112
	v_exp_f32_e32 v211, v113
	v_exp_f32_e32 v212, v114
	v_exp_f32_e32 v213, v115
	v_cvt_pkrtz_f16_f32 v120, v198, v199
	v_cvt_pkrtz_f16_f32 v121, v200, v201
	v_cvt_pkrtz_f16_f32 v122, v202, v203
	v_cvt_pkrtz_f16_f32 v123, v204, v205
	v_cvt_pkrtz_f16_f32 v124, v206, v207
	v_cvt_pkrtz_f16_f32 v125, v208, v209
	v_cvt_pkrtz_f16_f32 v126, v210, v211
	v_cvt_pkrtz_f16_f32 v127, v212, v213
	s_waitcnt lgkmcnt(0)
	s_and_b32 s44, s12, 2
	s_or_b32 s44, s44, 1
	v_mfma_f32_16x16x32_f16 v[100:103], v[96:99], v[8:11], v[128:131]
	s_add_i32 s8, s45, 64
	s_min_i32 s8, s8, s14
	s_mul_i32 s8, s8, s42
	v_mfma_f32_16x16x32_f16 v[104:107], v[88:91], v[8:11], v[128:131]
	s_mov_b32 s9, 0
	v_lshl_add_u64 v[238:239], v[240:241], 0, s[8:9]
	s_add_i32 m0, s22, 0x1b880
	s_nop 0
	v_mfma_f32_16x16x32_f16 v[108:111], v[96:99], v[16:19], v[132:135]
	global_load_lds_dwordx4 v[238:239], off
	s_add_i32 s45, s45, 32
	s_add_i32 s41, s41, -1
	v_mfma_f32_16x16x32_f16 v[112:115], v[88:91], v[16:19], v[132:135]
	s_add_i32 s10, s45, 0x9f
	s_cmp_gt_i32 s10, s51
	s_cselect_b32 s11, 2, 0
	s_add_i32 s10, s45, 0x1f1
	v_mfma_f32_16x16x32_f16 v[100:103], v[92:95], v[12:15], v[100:103]
	s_cmp_le_i32 s10, s51
	s_cselect_b32 s10, 2, 0
	s_and_b32 s10, s10, s4
	v_mfma_f32_16x16x32_f16 v[104:107], v[84:87], v[12:15], v[104:107]
	s_or_b32 s11, s11, s10
	s_lshr_b32 s10, s45, 6
	s_bitcmp1_b32 s39, s10
	s_cselect_b32 s10, 1, 0
	v_mfma_f32_16x16x32_f16 v[108:111], v[92:95], v[20:23], v[108:111]
	s_lshr_b32 s9, s11, 1
	s_or_b32 s10, s10, s9
	s_cmp_le_i32 s45, s15
	v_mfma_f32_16x16x32_f16 v[112:115], v[84:87], v[20:23], v[112:115]
	s_cselect_b32 s10, s10, 0
	s_cmp_ge_i32 s45, s40
	s_cselect_b32 s10, s10, 0
	s_or_b32 s12, s11, s10
	v_mfma_f32_16x16x32_f16 v[60:63], v[80:83], v[120:123], v[60:63]
	v_add_f32_e32 v214, v214, v198
	v_add_f32_e32 v215, v215, v199
	v_mfma_f32_16x16x32_f16 v[56:59], v[76:79], v[120:123], v[56:59]
	v_add_f32_e32 v216, v216, v200
	v_add_f32_e32 v217, v217, v201
	v_mfma_f32_16x16x32_f16 v[52:55], v[72:75], v[120:123], v[52:55]
	v_add_f32_e32 v214, v214, v202
	v_add_f32_e32 v215, v215, v203
	v_mfma_f32_16x16x32_f16 v[48:51], v[68:71], v[120:123], v[48:51]
	v_add_f32_e32 v216, v216, v204
	v_add_f32_e32 v217, v217, v205
	v_mfma_f32_16x16x32_f16 v[44:47], v[80:83], v[124:127], v[44:47]
	v_add_f32_e32 v218, v218, v206
	v_add_f32_e32 v219, v219, v207
	v_mfma_f32_16x16x32_f16 v[40:43], v[76:79], v[124:127], v[40:43]
	v_add_f32_e32 v220, v220, v208
	v_add_f32_e32 v221, v221, v209
	v_mfma_f32_16x16x32_f16 v[36:39], v[72:75], v[124:127], v[36:39]
	v_add_f32_e32 v218, v218, v210
	v_add_f32_e32 v219, v219, v211
	v_mfma_f32_16x16x32_f16 v[32:35], v[68:71], v[124:127], v[32:35]
	v_add_f32_e32 v220, v220, v212
	v_add_f32_e32 v221, v221, v213
	ds_read_b128 v[80:83], v65 offset:30720
	ds_read_b128 v[76:79], v65 offset:31744
	ds_read_b128 v[72:75], v65 offset:32768
	ds_read_b128 v[68:71], v65 offset:33792
	s_cmp_lg_u32 s41, 0
	s_cbranch_scc1 .Lat_xtop
	s_branch .Lat_xexit
.Lat_xb3:
	s_waitcnt lgkmcnt(0)
	s_and_b32 s44, s12, 2
	s_or_b32 s44, s44, 1
	v_mfma_f32_16x16x32_f16 v[100:103], v[96:99], v[8:11], v[128:131]
	s_add_i32 s8, s45, 64
	s_min_i32 s8, s8, s14
	s_mul_i32 s8, s8, s42
	v_mfma_f32_16x16x32_f16 v[104:107], v[88:91], v[8:11], v[128:131]
	s_mov_b32 s9, 0
	v_lshl_add_u64 v[238:239], v[240:241], 0, s[8:9]
	s_add_i32 m0, s22, 0x1b880
	s_nop 0
	v_mfma_f32_16x16x32_f16 v[108:111], v[96:99], v[16:19], v[132:135]
	global_load_lds_dwordx4 v[238:239], off
	s_add_i32 s45, s45, 32
	s_add_i32 s41, s41, -1
	v_mfma_f32_16x16x32_f16 v[112:115], v[88:91], v[16:19], v[132:135]
	s_add_i32 s10, s45, 0x9f
	s_cmp_gt_i32 s10, s51
	s_cselect_b32 s11, 2, 0
	s_add_i32 s10, s45, 0x1f1
	v_mfma_f32_16x16x32_f16 v[100:103], v[92:95], v[12:15], v[100:103]
	s_cmp_le_i32 s10, s51
	s_cselect_b32 s10, 2, 0
	s_and_b32 s10, s10, s4
	v_mfma_f32_16x16x32_f16 v[104:107], v[84:87], v[12:15], v[104:107]
	s_or_b32 s11, s11, s10
	s_lshr_b32 s10, s45, 6
	s_bitcmp1_b32 s39, s10
	s_cselect_b32 s10, 1, 0
	v_mfma_f32_16x16x32_f16 v[108:111], v[92:95], v[20:23], v[108:111]
	s_lshr_b32 s9, s11, 1
	s_or_b32 s10, s10, s9
	s_cmp_le_i32 s45, s15
	v_mfma_f32_16x16x32_f16 v[112:115], v[84:87], v[20:23], v[112:115]
	s_cselect_b32 s10, s10, 0
	s_cmp_ge_i32 s45, s40
	s_cselect_b32 s10, s10, 0
	s_or_b32 s12, s11, s10
	ds_read_b128 v[80:83], v65 offset:30720
	ds_read_b128 v[76:79], v65 offset:31744
	ds_read_b128 v[72:75], v65 offset:32768
	ds_read_b128 v[68:71], v65 offset:33792
	s_cmp_lg_u32 s41, 0
	s_cbranch_scc1 .Lat_xtop
	s_branch .Lat_xexit

; #define MFMA16(a, b, c) __builtin_amdgcn_mfma_f32_16x16x32_f16((a), (b), (c), 0, 0, 0)
; #define LAS __attribute__((address_space(3)))
; template <bool SEL, bool GEN>
; DI void attn_step(const KF& kv, const int kb, const int t, const int lane, const bool selbit,
;                   const LAS float* tabh, const half8 (&q)[2][2], f32x4 (&O)[2][4], const float (&nR)[2], float (&l)[2]) {
;     ...
;     for (int j = 0; j < 4; ++j) { p0[j] = __builtin_amdgcn_exp2f(s[hp][0][j]); p1[j] = __builtin_amdgcn_exp2f(s[hp][1][j]); }
;     l[hp] += ((p0[0] + p0[1]) + (p0[2] + p0[3])) + ((p1[0] + p1[1]) + (p1[2] + p1[3]));
;     pf[hp] = pack8(p0, p1);
;   }
; #pragma unroll
;   for (int dt = 0; dt < 4; ++dt)
; #pragma unroll
;     for (int hp = 0; hp < 2; ++hp) O[hp][dt] = MFMA16(kv.v[dt], pf[hp], O[hp][dt]);
; DI void attn_phase(const Params& p, const int layer, const int wid_s) {
;     ...
;         asm volatile("s_waitcnt vmcnt(0)" ::: "memory");
;         __syncthreads();
;         RING_ISSUE(0); RING_ISSUE(1);
; #pragma unroll 1
;         for (int si = 0; si < nsteps; ++si) {
;           asm volatile("s_waitcnt vmcnt(1) lgkmcnt(0)" ::: "memory");
;           __builtin_amdgcn_s_barrier();
;           asm volatile("" ::: "memory");
;           RING_ISSUE(si + 2);
;           const int kb = kb0 + si * 32;
;           if (kb > kmax_w || kb < lo_w) continue;
;           if (br == 1 && kb + 31 + 128 <= t0 && __ballot((selmask >> (kb >> 6)) & 1u) == 0ull) continue;
;           LAS unsigned char* slotp = ring + (si % 3) * 8192;
;           KF kv;
; #pragma unroll
;           for (int kt = 0; kt < 2; ++kt)
; #pragma unroll
;             for (int ks = 0; ks < 2; ++ks) kv.k[kt][ks] = *(const LAS half8*)(slotp + kread[kt][ks]);
; #pragma unroll
;           for (int dt = 0; dt < 4; ++dt) kv.v[dt] = *(const LAS half8*)(slotp + vread[dt]);
;           if (br == 1) {
;             const bool bit = (selmask >> (kb >> 6)) & 1u;
;             if (kb + 31 + 128 <= t0) attn_step<true, false>(kv, kb, t, lane, bit, tabh, q, O, nRs, l);
;             else attn_step<true, true>(kv, kb, t, lane, bit, tabh, q, O, nRs, l);
;           } else {
;             const bool gen = (kb + 31 + 128 > t0) || (kb + 512 <= t0 + 15);
.Lat_noga_xc3:
	v_exp_f32_e32 v198, v100
	v_exp_f32_e32 v199, v101
	v_exp_f32_e32 v200, v102
	v_exp_f32_e32 v201, v103
	v_exp_f32_e32 v202, v104
	v_exp_f32_e32 v203, v105
	v_exp_f32_e32 v204, v106
	v_exp_f32_e32 v205, v107
	v_exp_f32_e32 v206, v108
	v_exp_f32_e32 v207, v109
	v_exp_f32_e32 v208, v110
	v_exp_f32_e32 v209, v111
	v_exp_f32_e32 v210, v112
	v_exp_f32_e32 v211, v113
	v_exp_f32_e32 v212, v114
	v_exp_f32_e32 v213, v115
	v_cvt_pkrtz_f16_f32 v120, v198, v199
	v_cvt_pkrtz_f16_f32 v121, v200, v201
	v_cvt_pkrtz_f16_f32 v122, v202, v203
	v_cvt_pkrtz_f16_f32 v123, v204, v205
	v_cvt_pkrtz_f16_f32 v124, v206, v207
	v_cvt_pkrtz_f16_f32 v125, v208, v209
	v_cvt_pkrtz_f16_f32 v126, v210, v211
	v_cvt_pkrtz_f16_f32 v127, v212, v213
	s_waitcnt lgkmcnt(0)
	v_mfma_f32_16x16x32_f16 v[60:63], v[80:83], v[120:123], v[60:63]
	v_add_f32_e32 v214, v214, v198
	v_add_f32_e32 v215, v215, v199
	v_add_f32_e32 v216, v216, v200
	v_add_f32_e32 v217, v217, v201
	v_add_f32_e32 v214, v214, v202
	v_mfma_f32_16x16x32_f16 v[56:59], v[76:79], v[120:123], v[56:59]
	v_add_f32_e32 v215, v215, v203
	v_add_f32_e32 v216, v216, v204
	v_add_f32_e32 v217, v217, v205
	v_add_f32_e32 v218, v218, v206
	v_add_f32_e32 v219, v219, v207
	v_add_f32_e32 v220, v220, v208
	v_mfma_f32_16x16x32_f16 v[52:55], v[72:75], v[120:123], v[52:55]
	v_add_f32_e32 v221, v221, v209
	v_add_f32_e32 v218, v218, v210
	v_add_f32_e32 v219, v219, v211
	v_add_f32_e32 v220, v220, v212
	v_add_f32_e32 v221, v221, v213
	v_mfma_f32_16x16x32_f16 v[48:51], v[68:71], v[120:123], v[48:51]
	s_add_i32 s8, s45, 64
	s_min_i32 s8, s8, s14
	s_mul_i32 s8, s8, s42
	s_mov_b32 s9, 0
	v_lshl_add_u64 v[238:239], v[240:241], 0, s[8:9]
	s_add_i32 m0, s22, 0x1b880
	v_mfma_f32_16x16x32_f16 v[44:47], v[80:83], v[124:127], v[44:47]
	s_nop 0
	global_load_lds_dwordx4 v[238:239], off
	s_add_i32 s45, s45, 32
	s_add_i32 s41, s41, -1
	s_add_i32 s10, s45, 0x9f
	v_mfma_f32_16x16x32_f16 v[40:43], v[76:79], v[124:127], v[40:43]
	s_cmp_gt_i32 s10, s51
	s_cselect_b32 s11, 2, 0
	s_add_i32 s10, s45, 0x1f1
	s_cmp_le_i32 s10, s51
	s_cselect_b32 s10, 2, 0
	s_and_b32 s10, s10, s4
	v_mfma_f32_16x16x32_f16 v[36:39], v[72:75], v[124:127], v[36:39]
	s_or_b32 s11, s11, s10
	s_lshr_b32 s10, s45, 6
	s_bitcmp1_b32 s39, s10
	s_cselect_b32 s10, 1, 0
	s_lshr_b32 s9, s11, 1
	v_mfma_f32_16x16x32_f16 v[32:35], v[68:71], v[124:127], v[32:35]
	s_or_b32 s10, s10, s9
	s_cmp_le_i32 s45, s15
	s_cselect_b32 s10, s10, 0
	s_cmp_ge_i32 s45, s40
	s_cselect_b32 s10, s10, 0
	s_or_b32 s12, s11, s10
	s_mov_b32 s44, 0
	s_cmp_lg_u32 s41, 0
	s_cbranch_scc1 .Lat_xtop
	s_branch .Lat_xexit
.Lat_xd3:
	s_add_i32 s8, s45, 64
	s_min_i32 s8, s8, s14
	s_mul_i32 s8, s8, s42
	s_mov_b32 s9, 0
	v_lshl_add_u64 v[238:239], v[240:241], 0, s[8:9]
	s_add_i32 m0, s22, 0x1b880
	s_nop 0
	global_load_lds_dwordx4 v[238:239], off
	s_add_i32 s45, s45, 32
	s_add_i32 s41, s41, -1
	s_add_i32 s10, s45, 0x9f
	s_cmp_gt_i32 s10, s51
	s_cselect_b32 s11, 2, 0
	s_add_i32 s10, s45, 0x1f1
	s_cmp_le_i32 s10, s51
	s_cselect_b32 s10, 2, 0
	s_and_b32 s10, s10, s4
	s_or_b32 s11, s11, s10
	s_lshr_b32 s10, s45, 6
	s_bitcmp1_b32 s39, s10
	s_cselect_b32 s10, 1, 0
	s_lshr_b32 s9, s11, 1
	s_or_b32 s10, s10, s9
	s_cmp_le_i32 s45, s15
	s_cselect_b32 s10, s10, 0
	s_cmp_ge_i32 s45, s40
	s_cselect_b32 s10, s10, 0
	s_or_b32 s12, s11, s10
	s_cmp_lg_u32 s41, 0
	s_cbranch_scc1 .Lat_xtop
	s_branch .Lat_xexit

; template <bool SEL, bool GEN>
; DI void attn_step(const KF& kv, const int kb, const int t, const int lane, const bool selbit,
;                   const LAS float* tabh, const half8 (&q)[2][2], f32x4 (&O)[2][4], const float (&nR)[2], float (&l)[2]) {
;     ...
;   for (int hp = 0; hp < 2; ++hp) {
;     float nm = nR[hp];
;     if (SEL) nm = selbit ? nm : MASKV;
;     const f32x4 c0 = {nm, nm, nm, nm};
; #pragma unroll
;     for (int kt = 0; kt < 2; ++kt) {
;       s[hp][kt] = MFMA16(kv.k[kt][0], q[hp][0], c0);
;       s[hp][kt] = MFMA16(kv.k[kt][1], q[hp][1], s[hp][kt]);
;     }
;   }
;   if (GEN) {
;     const int d0 = t - kb - fq * 4;
; #pragma unroll
;     for (int kt = 0; kt < 2; ++kt)
; #pragma unroll
;       for (int j = 0; j < 4; ++j) {
;         const int dist = d0 - (kt * 16 + j);
;         const bool bad = SEL ? (dist < 0) : ((unsigned)dist >= 512u);
;         const int ix = bad ? 130 : (dist > 128 ? 128 : dist);
; #pragma unroll
;         for (int hp = 0; hp < 2; ++hp) s[hp][kt][j] += tabh[hp * 132 + ix];
;       }
;   }
;   half8 pf[2];
; #pragma unroll
;   for (int hp = 0; hp < 2; ++hp) {
;     f32x4 p0, p1;
; #pragma unroll
;     for (int j = 0; j < 4; ++j) { p0[j] = __builtin_amdgcn_exp2f(s[hp][0][j]); p1[j] = __builtin_amdgcn_exp2f(s[hp][1][j]); }
;     l[hp] += ((p0[0] + p0[1]) + (p0[2] + p0[3])) + ((p1[0] + p1[1]) + (p1[2] + p1[3]));
;     pf[hp] = pack8(p0, p1);
;   }
; #pragma unroll
;   for (int dt = 0; dt < 4; ++dt)
; #pragma unroll
;     for (int hp = 0; hp < 2; ++hp) O[hp][dt] = MFMA16(kv.v[dt], pf[hp], O[hp][dt]);
; DI void attn_phase(const Params& p, const int layer, const int wid_s) {
;     ...
;         asm volatile("s_waitcnt vmcnt(0)" ::: "memory");
;         __syncthreads();
;         RING_ISSUE(0); RING_ISSUE(1);
; #pragma unroll 1
;         for (int si = 0; si < nsteps; ++si) {
;           asm volatile("s_waitcnt vmcnt(1) lgkmcnt(0)" ::: "memory");
;           __builtin_amdgcn_s_barrier();
;           asm volatile("" ::: "memory");
;           RING_ISSUE(si + 2);
;           const int kb = kb0 + si * 32;
;           if (kb > kmax_w || kb < lo_w) continue;
;           if (br == 1 && kb + 31 + 128 <= t0 && __ballot((selmask >> (kb >> 6)) & 1u) == 0ull) continue;
;           LAS unsigned char* slotp = ring + (si % 3) * 8192;
;           KF kv;
; #pragma unroll
;           for (int kt = 0; kt < 2; ++kt)
; #pragma unroll
.Lat_cok_y0:
	s_bitcmp1_b32 s44, 0
	s_cbranch_scc0 .Lat_yb0
	s_waitcnt lgkmcnt(4)
	v_mfma_f32_16x16x32_f16 v[60:63], v[80:83], v[120:123], v[60:63]
	v_add_f32_e32 v214, v214, v198
	v_add_f32_e32 v215, v215, v199
	v_add_f32_e32 v216, v216, v200
	v_mfma_f32_16x16x32_f16 v[56:59], v[76:79], v[120:123], v[56:59]
	v_add_f32_e32 v217, v217, v201
	v_add_f32_e32 v214, v214, v202
	v_add_f32_e32 v215, v215, v203
	v_mfma_f32_16x16x32_f16 v[52:55], v[72:75], v[120:123], v[52:55]
	v_add_f32_e32 v216, v216, v204
	v_add_f32_e32 v217, v217, v205
	v_add_f32_e32 v218, v218, v206
	v_mfma_f32_16x16x32_f16 v[48:51], v[68:71], v[120:123], v[48:51]
	v_add_f32_e32 v219, v219, v207
	v_add_f32_e32 v220, v220, v208
	v_add_f32_e32 v221, v221, v209
	v_mfma_f32_16x16x32_f16 v[44:47], v[80:83], v[124:127], v[44:47]
	v_add_f32_e32 v218, v218, v210
	v_add_f32_e32 v219, v219, v211
	v_add_f32_e32 v220, v220, v212
	v_mfma_f32_16x16x32_f16 v[40:43], v[76:79], v[124:127], v[40:43]
	v_add_f32_e32 v221, v221, v213
	s_add_i32 s8, s45, 64
	s_min_i32 s8, s8, s14
	v_mfma_f32_16x16x32_f16 v[36:39], v[72:75], v[124:127], v[36:39]
	s_mul_i32 s8, s8, s42
	s_mov_b32 s9, 0
	v_lshl_add_u64 v[238:239], v[240:241], 0, s[8:9]
	v_mfma_f32_16x16x32_f16 v[32:35], v[68:71], v[124:127], v[32:35]
	s_add_i32 m0, s22, 0x1d880
	s_nop 0
	global_load_lds_dwordx4 v[238:239], off
	s_waitcnt lgkmcnt(0)
	s_and_b32 s44, s12, 2
	s_or_b32 s44, s44, 1
	v_mfma_f32_16x16x32_f16 v[100:103], v[96:99], v[8:11], v[128:131]
	s_add_i32 s45, s45, 32
	s_add_i32 s41, s41, -1
	v_mfma_f32_16x16x32_f16 v[104:107], v[88:91], v[8:11], v[128:131]
	s_add_i32 s10, s45, 0x9f
	s_cmp_gt_i32 s10, s51
	s_cselect_b32 s11, 2, 0
	v_mfma_f32_16x16x32_f16 v[108:111], v[96:99], v[16:19], v[132:135]
	s_add_i32 s10, s45, 0x1f1
	s_cmp_le_i32 s10, s51
	v_mfma_f32_16x16x32_f16 v[112:115], v[88:91], v[16:19], v[132:135]
	s_cselect_b32 s10, 2, 0
	s_and_b32 s10, s10, s4
	s_or_b32 s11, s11, s10
	v_mfma_f32_16x16x32_f16 v[100:103], v[92:95], v[12:15], v[100:103]
	s_lshr_b32 s10, s45, 6
	s_bitcmp1_b32 s39, s10
	v_mfma_f32_16x16x32_f16 v[104:107], v[84:87], v[12:15], v[104:107]
	s_cselect_b32 s10, 1, 0
	s_lshr_b32 s9, s11, 1
	s_or_b32 s10, s10, s9
	v_mfma_f32_16x16x32_f16 v[108:111], v[92:95], v[20:23], v[108:111]
	s_cmp_le_i32 s45, s15
	s_cselect_b32 s10, s10, 0
	v_mfma_f32_16x16x32_f16 v[112:115], v[84:87], v[20:23], v[112:115]
	s_cmp_ge_i32 s45, s40
	s_cselect_b32 s10, s10, 0
	s_or_b32 s12, s11, s10
	ds_read_b128 v[80:83], v65 offset:4096
	ds_read_b128 v[76:79], v65 offset:5120
	ds_read_b128 v[72:75], v65 offset:6144
	ds_read_b128 v[68:71], v65 offset:7168
	s_bitcmp1_b32 s44, 1
	s_cbranch_scc0 .Lat_noga_ya0
	v_add_f32_e32 v100, v100, v222
	v_add_f32_e32 v101, v101, v223
	v_add_f32_e32 v102, v102, v224
	v_add_f32_e32 v103, v103, v225
	v_add_f32_e32 v104, v104, v226
	v_add_f32_e32 v105, v105, v227
	v_add_f32_e32 v106, v106, v228
	v_add_f32_e32 v107, v107, v229
	v_add_f32_e32 v108, v108, v230
	v_add_f32_e32 v109, v109, v231
	v_add_f32_e32 v110, v110, v232
	v_add_f32_e32 v111, v111, v233
	v_add_f32_e32 v112, v112, v234
	v_add_f32_e32 v113, v113, v235
	v_add_f32_e32 v114, v114, v236
	v_add_f32_e32 v115, v115, v237

; template <bool SEL, bool GEN>
; DI void attn_step(const KF& kv, const int kb, const int t, const int lane, const bool selbit,
;                   const LAS float* tabh, const half8 (&q)[2][2], f32x4 (&O)[2][4], const float (&nR)[2], float (&l)[2]) {
;     ...
;   for (int hp = 0; hp < 2; ++hp) {
;     float nm = nR[hp];
;     if (SEL) nm = selbit ? nm : MASKV;
;     const f32x4 c0 = {nm, nm, nm, nm};
; #pragma unroll
;     for (int kt = 0; kt < 2; ++kt) {
;       s[hp][kt] = MFMA16(kv.k[kt][0], q[hp][0], c0);
;       s[hp][kt] = MFMA16(kv.k[kt][1], q[hp][1], s[hp][kt]);
;     }
;   }
;   if (GEN) {
;     const int d0 = t - kb - fq * 4;
; #pragma unroll
;     for (int kt = 0; kt < 2; ++kt)
; #pragma unroll
;       for (int j = 0; j < 4; ++j) {
;         const int dist = d0 - (kt * 16 + j);
;         const bool bad = SEL ? (dist < 0) : ((unsigned)dist >= 512u);
;         const int ix = bad ? 130 : (dist > 128 ? 128 : dist);
; #pragma unroll
;         for (int hp = 0; hp < 2; ++hp) s[hp][kt][j] += tabh[hp * 132 + ix];
;       }
; DI void attn_phase(const Params& p, const int layer, const int wid_s) {
;     ...
;         asm volatile("s_waitcnt vmcnt(0)" ::: "memory");
;         __syncthreads();
;         RING_ISSUE(0); RING_ISSUE(1);
; #pragma unroll 1
;         for (int si = 0; si < nsteps; ++si) {
;           asm volatile("s_waitcnt vmcnt(1) lgkmcnt(0)" ::: "memory");
;           __builtin_amdgcn_s_barrier();
;           asm volatile("" ::: "memory");
;           RING_ISSUE(si + 2);
;           const int kb = kb0 + si * 32;
;           if (kb > kmax_w || kb < lo_w) continue;
;           if (br == 1 && kb + 31 + 128 <= t0 && __ballot((selmask >> (kb >> 6)) & 1u) == 0ull) continue;
;           LAS unsigned char* slotp = ring + (si % 3) * 8192;
;           KF kv;
; #pragma unroll
;           for (int kt = 0; kt < 2; ++kt)
; #pragma unroll
;             for (int ks = 0; ks < 2; ++ks) kv.k[kt][ks] = *(const LAS half8*)(slotp + kread[kt][ks]);
; #pragma unroll
;           for (int dt = 0; dt < 4; ++dt) kv.v[dt] = *(const LAS half8*)(slotp + vread[dt]);
;           if (br == 1) {
;             const bool bit = (selmask >> (kb >> 6)) & 1u;
;             if (kb + 31 + 128 <= t0) attn_step<true, false>(kv, kb, t, lane, bit, tabh, q, O, nRs, l);
;             else attn_step<true, true>(kv, kb, t, lane, bit, tabh, q, O, nRs, l);
;           } else {
.Lat_yb0:
	s_waitcnt lgkmcnt(0)
	s_and_b32 s44, s12, 2
	s_or_b32 s44, s44, 1
	v_mfma_f32_16x16x32_f16 v[100:103], v[96:99], v[8:11], v[128:131]
	s_add_i32 s8, s45, 64
	s_min_i32 s8, s8, s14
	s_mul_i32 s8, s8, s42
	v_mfma_f32_16x16x32_f16 v[104:107], v[88:91], v[8:11], v[128:131]
	s_mov_b32 s9, 0
	v_lshl_add_u64 v[238:239], v[240:241], 0, s[8:9]
	s_add_i32 m0, s22, 0x1d880
	s_nop 0
	v_mfma_f32_16x16x32_f16 v[108:111], v[96:99], v[16:19], v[132:135]
	global_load_lds_dwordx4 v[238:239], off
	s_add_i32 s45, s45, 32
	s_add_i32 s41, s41, -1
	v_mfma_f32_16x16x32_f16 v[112:115], v[88:91], v[16:19], v[132:135]
	s_add_i32 s10, s45, 0x9f
	s_cmp_gt_i32 s10, s51
	s_cselect_b32 s11, 2, 0
	s_add_i32 s10, s45, 0x1f1
	v_mfma_f32_16x16x32_f16 v[100:103], v[92:95], v[12:15], v[100:103]
	s_cmp_le_i32 s10, s51
	s_cselect_b32 s10, 2, 0
	s_and_b32 s10, s10, s4
	v_mfma_f32_16x16x32_f16 v[104:107], v[84:87], v[12:15], v[104:107]
	s_or_b32 s11, s11, s10
	s_lshr_b32 s10, s45, 6
	s_bitcmp1_b32 s39, s10
	s_cselect_b32 s10, 1, 0
	v_mfma_f32_16x16x32_f16 v[108:111], v[92:95], v[20:23], v[108:111]
	s_lshr_b32 s9, s11, 1
	s_or_b32 s10, s10, s9
	s_cmp_le_i32 s45, s15
	v_mfma_f32_16x16x32_f16 v[112:115], v[84:87], v[20:23], v[112:115]
	s_cselect_b32 s10, s10, 0
	s_cmp_ge_i32 s45, s40
	s_cselect_b32 s10, s10, 0
	s_or_b32 s12, s11, s10
	ds_read_b128 v[80:83], v65 offset:4096
	ds_read_b128 v[76:79], v65 offset:5120
	ds_read_b128 v[72:75], v65 offset:6144
	ds_read_b128 v[68:71], v65 offset:7168
	s_bitcmp1_b32 s44, 1
	s_cbranch_scc0 .Lat_noga_yb0
	v_add_f32_e32 v100, v100, v222
	v_add_f32_e32 v101, v101, v223
	v_add_f32_e32 v102, v102, v224
	v_add_f32_e32 v103, v103, v225
	v_add_f32_e32 v104, v104, v226
	v_add_f32_e32 v105, v105, v227
	v_add_f32_e32 v106, v106, v228
	v_add_f32_e32 v107, v107, v229
	v_add_f32_e32 v108, v108, v230
	v_add_f32_e32 v109, v109, v231
	v_add_f32_e32 v110, v110, v232
	v_add_f32_e32 v111, v111, v233
	v_add_f32_e32 v112, v112, v234
	v_add_f32_e32 v113, v113, v235
	v_add_f32_e32 v114, v114, v236
	v_add_f32_e32 v115, v115, v237

; #define MFMA16(a, b, c) __builtin_amdgcn_mfma_f32_16x16x32_f16((a), (b), (c), 0, 0, 0)
; #define LAS __attribute__((address_space(3)))
; template <bool SEL, bool GEN>
; DI void attn_step(const KF& kv, const int kb, const int t, const int lane, const bool selbit,
;                   const LAS float* tabh, const half8 (&q)[2][2], f32x4 (&O)[2][4], const float (&nR)[2], float (&l)[2]) {
;     ...
;     for (int j = 0; j < 4; ++j) { p0[j] = __builtin_amdgcn_exp2f(s[hp][0][j]); p1[j] = __builtin_amdgcn_exp2f(s[hp][1][j]); }
;     l[hp] += ((p0[0] + p0[1]) + (p0[2] + p0[3])) + ((p1[0] + p1[1]) + (p1[2] + p1[3]));
;     pf[hp] = pack8(p0, p1);
;   }
; #pragma unroll
;   for (int dt = 0; dt < 4; ++dt)
; #pragma unroll
;     for (int hp = 0; hp < 2; ++hp) O[hp][dt] = MFMA16(kv.v[dt], pf[hp], O[hp][dt]);
; DI void attn_phase(const Params& p, const int layer, const int wid_s) {
;     ...
;         asm volatile("s_waitcnt vmcnt(0)" ::: "memory");
;         __syncthreads();
;         RING_ISSUE(0); RING_ISSUE(1);
; #pragma unroll 1
;         for (int si = 0; si < nsteps; ++si) {
;           asm volatile("s_waitcnt vmcnt(1) lgkmcnt(0)" ::: "memory");
;           __builtin_amdgcn_s_barrier();
;           asm volatile("" ::: "memory");
;           RING_ISSUE(si + 2);
;           const int kb = kb0 + si * 32;
;           if (kb > kmax_w || kb < lo_w) continue;
;           if (br == 1 && kb + 31 + 128 <= t0 && __ballot((selmask >> (kb >> 6)) & 1u) == 0ull) continue;
;           LAS unsigned char* slotp = ring + (si % 3) * 8192;
;           KF kv;
; #pragma unroll
;           for (int kt = 0; kt < 2; ++kt)
; #pragma unroll
;             for (int ks = 0; ks < 2; ++ks) kv.k[kt][ks] = *(const LAS half8*)(slotp + kread[kt][ks]);
; #pragma unroll
;           for (int dt = 0; dt < 4; ++dt) kv.v[dt] = *(const LAS half8*)(slotp + vread[dt]);
;           if (br == 1) {
;             const bool bit = (selmask >> (kb >> 6)) & 1u;
;             if (kb + 31 + 128 <= t0) attn_step<true, false>(kv, kb, t, lane, bit, tabh, q, O, nRs, l);
;             else attn_step<true, true>(kv, kb, t, lane, bit, tabh, q, O, nRs, l);
;           } else {
;             const bool gen = (kb + 31 + 128 > t0) || (kb + 512 <= t0 + 15);
.Lat_yskip0:
	s_bitcmp1_b32 s44, 0
	s_cbranch_scc0 .Lat_yd0
	s_waitcnt lgkmcnt(0)
	v_mfma_f32_16x16x32_f16 v[60:63], v[80:83], v[120:123], v[60:63]
	v_add_f32_e32 v214, v214, v198
	v_add_f32_e32 v215, v215, v199
	v_add_f32_e32 v216, v216, v200
	v_add_f32_e32 v217, v217, v201
	v_add_f32_e32 v214, v214, v202
	v_mfma_f32_16x16x32_f16 v[56:59], v[76:79], v[120:123], v[56:59]
	v_add_f32_e32 v215, v215, v203
	v_add_f32_e32 v216, v216, v204
	v_add_f32_e32 v217, v217, v205
	v_add_f32_e32 v218, v218, v206
	v_add_f32_e32 v219, v219, v207
	v_add_f32_e32 v220, v220, v208
	v_mfma_f32_16x16x32_f16 v[52:55], v[72:75], v[120:123], v[52:55]
	v_add_f32_e32 v221, v221, v209
	v_add_f32_e32 v218, v218, v210
	v_add_f32_e32 v219, v219, v211
	v_add_f32_e32 v220, v220, v212
	v_add_f32_e32 v221, v221, v213
	v_mfma_f32_16x16x32_f16 v[48:51], v[68:71], v[120:123], v[48:51]
	s_add_i32 s8, s45, 64
	s_min_i32 s8, s8, s14
	s_mul_i32 s8, s8, s42
	s_mov_b32 s9, 0
	v_lshl_add_u64 v[238:239], v[240:241], 0, s[8:9]
	s_add_i32 m0, s22, 0x1d880
	v_mfma_f32_16x16x32_f16 v[44:47], v[80:83], v[124:127], v[44:47]
	s_nop 0
	global_load_lds_dwordx4 v[238:239], off
	s_add_i32 s45, s45, 32
	s_add_i32 s41, s41, -1
	s_add_i32 s10, s45, 0x9f
	v_mfma_f32_16x16x32_f16 v[40:43], v[76:79], v[124:127], v[40:43]
	s_cmp_gt_i32 s10, s51
	s_cselect_b32 s11, 2, 0
	s_add_i32 s10, s45, 0x1f1
	s_cmp_le_i32 s10, s51
	s_cselect_b32 s10, 2, 0
	s_and_b32 s10, s10, s4
	v_mfma_f32_16x16x32_f16 v[36:39], v[72:75], v[124:127], v[36:39]
	s_or_b32 s11, s11, s10
	s_lshr_b32 s10, s45, 6
	s_bitcmp1_b32 s39, s10
	s_cselect_b32 s10, 1, 0
	s_lshr_b32 s9, s11, 1
	v_mfma_f32_16x16x32_f16 v[32:35], v[68:71], v[124:127], v[32:35]
	s_or_b32 s10, s10, s9
	s_cmp_le_i32 s45, s15
	s_cselect_b32 s10, s10, 0
	s_cmp_ge_i32 s45, s40
	s_cselect_b32 s10, s10, 0
	s_or_b32 s12, s11, s10
	s_mov_b32 s44, 0
	s_cmp_lg_u32 s41, 0
	s_cbranch_scc1 .Lat_ytop1
	s_branch .Lat_yexit

; template <bool SEL, bool GEN>
; DI void attn_step(const KF& kv, const int kb, const int t, const int lane, const bool selbit,
;                   const LAS float* tabh, const half8 (&q)[2][2], f32x4 (&O)[2][4], const float (&nR)[2], float (&l)[2]) {
;     ...
;   for (int hp = 0; hp < 2; ++hp) {
;     float nm = nR[hp];
;     if (SEL) nm = selbit ? nm : MASKV;
;     const f32x4 c0 = {nm, nm, nm, nm};
; #pragma unroll
;     for (int kt = 0; kt < 2; ++kt) {
;       s[hp][kt] = MFMA16(kv.k[kt][0], q[hp][0], c0);
;       s[hp][kt] = MFMA16(kv.k[kt][1], q[hp][1], s[hp][kt]);
;     }
;   }
;   if (GEN) {
;     const int d0 = t - kb - fq * 4;
; #pragma unroll
;     for (int kt = 0; kt < 2; ++kt)
; #pragma unroll
;       for (int j = 0; j < 4; ++j) {
;         const int dist = d0 - (kt * 16 + j);
;         const bool bad = SEL ? (dist < 0) : ((unsigned)dist >= 512u);
;         const int ix = bad ? 130 : (dist > 128 ? 128 : dist);
; #pragma unroll
;         for (int hp = 0; hp < 2; ++hp) s[hp][kt][j] += tabh[hp * 132 + ix];
;       }
;   }
;   half8 pf[2];
; #pragma unroll
;   for (int hp = 0; hp < 2; ++hp) {
;     f32x4 p0, p1;
; #pragma unroll
;     for (int j = 0; j < 4; ++j) { p0[j] = __builtin_amdgcn_exp2f(s[hp][0][j]); p1[j] = __builtin_amdgcn_exp2f(s[hp][1][j]); }
;     l[hp] += ((p0[0] + p0[1]) + (p0[2] + p0[3])) + ((p1[0] + p1[1]) + (p1[2] + p1[3]));
;     pf[hp] = pack8(p0, p1);
;   }
; #pragma unroll
;   for (int dt = 0; dt < 4; ++dt)
; #pragma unroll
;     for (int hp = 0; hp < 2; ++hp) O[hp][dt] = MFMA16(kv.v[dt], pf[hp], O[hp][dt]);
; DI void attn_phase(const Params& p, const int layer, const int wid_s) {
;     ...
;         asm volatile("s_waitcnt vmcnt(0)" ::: "memory");
;         __syncthreads();
;         RING_ISSUE(0); RING_ISSUE(1);
; #pragma unroll 1
;         for (int si = 0; si < nsteps; ++si) {
;           asm volatile("s_waitcnt vmcnt(1) lgkmcnt(0)" ::: "memory");
;           __builtin_amdgcn_s_barrier();
;           asm volatile("" ::: "memory");
;           RING_ISSUE(si + 2);
;           const int kb = kb0 + si * 32;
;           if (kb > kmax_w || kb < lo_w) continue;
;           if (br == 1 && kb + 31 + 128 <= t0 && __ballot((selmask >> (kb >> 6)) & 1u) == 0ull) continue;
;           LAS unsigned char* slotp = ring + (si % 3) * 8192;
;           KF kv;
; #pragma unroll
;           for (int kt = 0; kt < 2; ++kt)
; #pragma unroll
.Lat_cok_y1:
	s_bitcmp1_b32 s44, 0
	s_cbranch_scc0 .Lat_yb1
	s_waitcnt lgkmcnt(4)
	v_mfma_f32_16x16x32_f16 v[60:63], v[80:83], v[120:123], v[60:63]
	v_add_f32_e32 v214, v214, v198
	v_add_f32_e32 v215, v215, v199
	v_add_f32_e32 v216, v216, v200
	v_mfma_f32_16x16x32_f16 v[56:59], v[76:79], v[120:123], v[56:59]
	v_add_f32_e32 v217, v217, v201
	v_add_f32_e32 v214, v214, v202
	v_add_f32_e32 v215, v215, v203
	v_mfma_f32_16x16x32_f16 v[52:55], v[72:75], v[120:123], v[52:55]
	v_add_f32_e32 v216, v216, v204
	v_add_f32_e32 v217, v217, v205
	v_add_f32_e32 v218, v218, v206
	v_mfma_f32_16x16x32_f16 v[48:51], v[68:71], v[120:123], v[48:51]
	v_add_f32_e32 v219, v219, v207
	v_add_f32_e32 v220, v220, v208
	v_add_f32_e32 v221, v221, v209
	v_mfma_f32_16x16x32_f16 v[44:47], v[80:83], v[124:127], v[44:47]
	v_add_f32_e32 v218, v218, v210
	v_add_f32_e32 v219, v219, v211
	v_add_f32_e32 v220, v220, v212
	v_mfma_f32_16x16x32_f16 v[40:43], v[76:79], v[124:127], v[40:43]
	v_add_f32_e32 v221, v221, v213
	s_add_i32 s8, s45, 64
	s_min_i32 s8, s8, s14
	v_mfma_f32_16x16x32_f16 v[36:39], v[72:75], v[124:127], v[36:39]
	s_mul_i32 s8, s8, s42
	s_mov_b32 s9, 0
	v_lshl_add_u64 v[238:239], v[240:241], 0, s[8:9]
	v_mfma_f32_16x16x32_f16 v[32:35], v[68:71], v[124:127], v[32:35]
	s_add_i32 m0, s22, 0x20080
	s_nop 0
	global_load_lds_dwordx4 v[238:239], off
	s_waitcnt lgkmcnt(0)
	s_and_b32 s44, s12, 2
	s_or_b32 s44, s44, 1
	v_mfma_f32_16x16x32_f16 v[100:103], v[96:99], v[8:11], v[128:131]
	s_add_i32 s45, s45, 32
	s_add_i32 s41, s41, -1
	v_mfma_f32_16x16x32_f16 v[104:107], v[88:91], v[8:11], v[128:131]
	s_add_i32 s10, s45, 0x9f
	s_cmp_gt_i32 s10, s51
	s_cselect_b32 s11, 2, 0
	v_mfma_f32_16x16x32_f16 v[108:111], v[96:99], v[16:19], v[132:135]
	s_add_i32 s10, s45, 0x1f1
	s_cmp_le_i32 s10, s51
	v_mfma_f32_16x16x32_f16 v[112:115], v[88:91], v[16:19], v[132:135]
	s_cselect_b32 s10, 2, 0
	s_and_b32 s10, s10, s4
	s_or_b32 s11, s11, s10
	v_mfma_f32_16x16x32_f16 v[100:103], v[92:95], v[12:15], v[100:103]
	s_lshr_b32 s10, s45, 6
	s_bitcmp1_b32 s39, s10
	v_mfma_f32_16x16x32_f16 v[104:107], v[84:87], v[12:15], v[104:107]
	s_cselect_b32 s10, 1, 0
	s_lshr_b32 s9, s11, 1
	s_or_b32 s10, s10, s9
	v_mfma_f32_16x16x32_f16 v[108:111], v[92:95], v[20:23], v[108:111]
	s_cmp_le_i32 s45, s15
	s_cselect_b32 s10, s10, 0
	v_mfma_f32_16x16x32_f16 v[112:115], v[84:87], v[20:23], v[112:115]
	s_cmp_ge_i32 s45, s40
	s_cselect_b32 s10, s10, 0
	s_or_b32 s12, s11, s10
	ds_read_b128 v[80:83], v65 offset:12288
	ds_read_b128 v[76:79], v65 offset:13312
	ds_read_b128 v[72:75], v65 offset:14336
	ds_read_b128 v[68:71], v65 offset:15360
	s_bitcmp1_b32 s44, 1
	s_cbranch_scc0 .Lat_noga_ya1
	v_add_f32_e32 v100, v100, v222
	v_add_f32_e32 v101, v101, v223
	v_add_f32_e32 v102, v102, v224
	v_add_f32_e32 v103, v103, v225
	v_add_f32_e32 v104, v104, v226
	v_add_f32_e32 v105, v105, v227
	v_add_f32_e32 v106, v106, v228
	v_add_f32_e32 v107, v107, v229
	v_add_f32_e32 v108, v108, v230
	v_add_f32_e32 v109, v109, v231
	v_add_f32_e32 v110, v110, v232
	v_add_f32_e32 v111, v111, v233
	v_add_f32_e32 v112, v112, v234
	v_add_f32_e32 v113, v113, v235
	v_add_f32_e32 v114, v114, v236
	v_add_f32_e32 v115, v115, v237

; template <bool SEL, bool GEN>
; DI void attn_step(const KF& kv, const int kb, const int t, const int lane, const bool selbit,
;                   const LAS float* tabh, const half8 (&q)[2][2], f32x4 (&O)[2][4], const float (&nR)[2], float (&l)[2]) {
;     ...
;   for (int hp = 0; hp < 2; ++hp) {
;     float nm = nR[hp];
;     if (SEL) nm = selbit ? nm : MASKV;
;     const f32x4 c0 = {nm, nm, nm, nm};
; #pragma unroll
;     for (int kt = 0; kt < 2; ++kt) {
;       s[hp][kt] = MFMA16(kv.k[kt][0], q[hp][0], c0);
;       s[hp][kt] = MFMA16(kv.k[kt][1], q[hp][1], s[hp][kt]);
;     }
;   }
;   if (GEN) {
;     const int d0 = t - kb - fq * 4;
; #pragma unroll
;     for (int kt = 0; kt < 2; ++kt)
; #pragma unroll
;       for (int j = 0; j < 4; ++j) {
;         const int dist = d0 - (kt * 16 + j);
;         const bool bad = SEL ? (dist < 0) : ((unsigned)dist >= 512u);
;         const int ix = bad ? 130 : (dist > 128 ? 128 : dist);
; #pragma unroll
;         for (int hp = 0; hp < 2; ++hp) s[hp][kt][j] += tabh[hp * 132 + ix];
;       }
; DI void attn_phase(const Params& p, const int layer, const int wid_s) {
;     ...
;         asm volatile("s_waitcnt vmcnt(0)" ::: "memory");
;         __syncthreads();
;         RING_ISSUE(0); RING_ISSUE(1);
; #pragma unroll 1
;         for (int si = 0; si < nsteps; ++si) {
;           asm volatile("s_waitcnt vmcnt(1) lgkmcnt(0)" ::: "memory");
;           __builtin_amdgcn_s_barrier();
;           asm volatile("" ::: "memory");
;           RING_ISSUE(si + 2);
;           const int kb = kb0 + si * 32;
;           if (kb > kmax_w || kb < lo_w) continue;
;           if (br == 1 && kb + 31 + 128 <= t0 && __ballot((selmask >> (kb >> 6)) & 1u) == 0ull) continue;
;           LAS unsigned char* slotp = ring + (si % 3) * 8192;
;           KF kv;
; #pragma unroll
;           for (int kt = 0; kt < 2; ++kt)
; #pragma unroll
;             for (int ks = 0; ks < 2; ++ks) kv.k[kt][ks] = *(const LAS half8*)(slotp + kread[kt][ks]);
; #pragma unroll
;           for (int dt = 0; dt < 4; ++dt) kv.v[dt] = *(const LAS half8*)(slotp + vread[dt]);
;           if (br == 1) {
;             const bool bit = (selmask >> (kb >> 6)) & 1u;
;             if (kb + 31 + 128 <= t0) attn_step<true, false>(kv, kb, t, lane, bit, tabh, q, O, nRs, l);
;             else attn_step<true, true>(kv, kb, t, lane, bit, tabh, q, O, nRs, l);
;           } else {
.Lat_yb1:
	s_waitcnt lgkmcnt(0)
	s_and_b32 s44, s12, 2
	s_or_b32 s44, s44, 1
	v_mfma_f32_16x16x32_f16 v[100:103], v[96:99], v[8:11], v[128:131]
	s_add_i32 s8, s45, 64
	s_min_i32 s8, s8, s14
	s_mul_i32 s8, s8, s42
	v_mfma_f32_16x16x32_f16 v[104:107], v[88:91], v[8:11], v[128:131]
	s_mov_b32 s9, 0
	v_lshl_add_u64 v[238:239], v[240:241], 0, s[8:9]
	s_add_i32 m0, s22, 0x20080
	s_nop 0
	v_mfma_f32_16x16x32_f16 v[108:111], v[96:99], v[16:19], v[132:135]
	global_load_lds_dwordx4 v[238:239], off
	s_add_i32 s45, s45, 32
	s_add_i32 s41, s41, -1
	v_mfma_f32_16x16x32_f16 v[112:115], v[88:91], v[16:19], v[132:135]
	s_add_i32 s10, s45, 0x9f
	s_cmp_gt_i32 s10, s51
	s_cselect_b32 s11, 2, 0
	s_add_i32 s10, s45, 0x1f1
	v_mfma_f32_16x16x32_f16 v[100:103], v[92:95], v[12:15], v[100:103]
	s_cmp_le_i32 s10, s51
	s_cselect_b32 s10, 2, 0
	s_and_b32 s10, s10, s4
	v_mfma_f32_16x16x32_f16 v[104:107], v[84:87], v[12:15], v[104:107]
	s_or_b32 s11, s11, s10
	s_lshr_b32 s10, s45, 6
	s_bitcmp1_b32 s39, s10
	s_cselect_b32 s10, 1, 0
	v_mfma_f32_16x16x32_f16 v[108:111], v[92:95], v[20:23], v[108:111]
	s_lshr_b32 s9, s11, 1
	s_or_b32 s10, s10, s9
	s_cmp_le_i32 s45, s15
	v_mfma_f32_16x16x32_f16 v[112:115], v[84:87], v[20:23], v[112:115]
	s_cselect_b32 s10, s10, 0
	s_cmp_ge_i32 s45, s40
	s_cselect_b32 s10, s10, 0
	s_or_b32 s12, s11, s10
	ds_read_b128 v[80:83], v65 offset:12288
	ds_read_b128 v[76:79], v65 offset:13312
	ds_read_b128 v[72:75], v65 offset:14336
	ds_read_b128 v[68:71], v65 offset:15360
	s_bitcmp1_b32 s44, 1
	s_cbranch_scc0 .Lat_noga_yb1
	v_add_f32_e32 v100, v100, v222
	v_add_f32_e32 v101, v101, v223
	v_add_f32_e32 v102, v102, v224
	v_add_f32_e32 v103, v103, v225
	v_add_f32_e32 v104, v104, v226
	v_add_f32_e32 v105, v105, v227
	v_add_f32_e32 v106, v106, v228
	v_add_f32_e32 v107, v107, v229
	v_add_f32_e32 v108, v108, v230
	v_add_f32_e32 v109, v109, v231
	v_add_f32_e32 v110, v110, v232
	v_add_f32_e32 v111, v111, v233
	v_add_f32_e32 v112, v112, v234
	v_add_f32_e32 v113, v113, v235
	v_add_f32_e32 v114, v114, v236
	v_add_f32_e32 v115, v115, v237

; #define MFMA16(a, b, c) __builtin_amdgcn_mfma_f32_16x16x32_f16((a), (b), (c), 0, 0, 0)
; #define LAS __attribute__((address_space(3)))
; template <bool SEL, bool GEN>
; DI void attn_step(const KF& kv, const int kb, const int t, const int lane, const bool selbit,
;                   const LAS float* tabh, const half8 (&q)[2][2], f32x4 (&O)[2][4], const float (&nR)[2], float (&l)[2]) {
;     ...
;     for (int j = 0; j < 4; ++j) { p0[j] = __builtin_amdgcn_exp2f(s[hp][0][j]); p1[j] = __builtin_amdgcn_exp2f(s[hp][1][j]); }
;     l[hp] += ((p0[0] + p0[1]) + (p0[2] + p0[3])) + ((p1[0] + p1[1]) + (p1[2] + p1[3]));
;     pf[hp] = pack8(p0, p1);
;   }
; #pragma unroll
;   for (int dt = 0; dt < 4; ++dt)
; #pragma unroll
;     for (int hp = 0; hp < 2; ++hp) O[hp][dt] = MFMA16(kv.v[dt], pf[hp], O[hp][dt]);
; DI void attn_phase(const Params& p, const int layer, const int wid_s) {
;     ...
;         asm volatile("s_waitcnt vmcnt(0)" ::: "memory");
;         __syncthreads();
;         RING_ISSUE(0); RING_ISSUE(1);
; #pragma unroll 1
;         for (int si = 0; si < nsteps; ++si) {
;           asm volatile("s_waitcnt vmcnt(1) lgkmcnt(0)" ::: "memory");
;           __builtin_amdgcn_s_barrier();
;           asm volatile("" ::: "memory");
;           RING_ISSUE(si + 2);
;           const int kb = kb0 + si * 32;
;           if (kb > kmax_w || kb < lo_w) continue;
;           if (br == 1 && kb + 31 + 128 <= t0 && __ballot((selmask >> (kb >> 6)) & 1u) == 0ull) continue;
;           LAS unsigned char* slotp = ring + (si % 3) * 8192;
;           KF kv;
; #pragma unroll
;           for (int kt = 0; kt < 2; ++kt)
; #pragma unroll
;             for (int ks = 0; ks < 2; ++ks) kv.k[kt][ks] = *(const LAS half8*)(slotp + kread[kt][ks]);
; #pragma unroll
;           for (int dt = 0; dt < 4; ++dt) kv.v[dt] = *(const LAS half8*)(slotp + vread[dt]);
;           if (br == 1) {
;             const bool bit = (selmask >> (kb >> 6)) & 1u;
;             if (kb + 31 + 128 <= t0) attn_step<true, false>(kv, kb, t, lane, bit, tabh, q, O, nRs, l);
;             else attn_step<true, true>(kv, kb, t, lane, bit, tabh, q, O, nRs, l);
;           } else {
;             const bool gen = (kb + 31 + 128 > t0) || (kb + 512 <= t0 + 15);
.Lat_yskip1:
	s_bitcmp1_b32 s44, 0
	s_cbranch_scc0 .Lat_yd1
	s_waitcnt lgkmcnt(0)
	v_mfma_f32_16x16x32_f16 v[60:63], v[80:83], v[120:123], v[60:63]
	v_add_f32_e32 v214, v214, v198
	v_add_f32_e32 v215, v215, v199
	v_add_f32_e32 v216, v216, v200
	v_add_f32_e32 v217, v217, v201
	v_add_f32_e32 v214, v214, v202
	v_mfma_f32_16x16x32_f16 v[56:59], v[76:79], v[120:123], v[56:59]
	v_add_f32_e32 v215, v215, v203
	v_add_f32_e32 v216, v216, v204
	v_add_f32_e32 v217, v217, v205
	v_add_f32_e32 v218, v218, v206
	v_add_f32_e32 v219, v219, v207
	v_add_f32_e32 v220, v220, v208
	v_mfma_f32_16x16x32_f16 v[52:55], v[72:75], v[120:123], v[52:55]
	v_add_f32_e32 v221, v221, v209
	v_add_f32_e32 v218, v218, v210
	v_add_f32_e32 v219, v219, v211
	v_add_f32_e32 v220, v220, v212
	v_add_f32_e32 v221, v221, v213
	v_mfma_f32_16x16x32_f16 v[48:51], v[68:71], v[120:123], v[48:51]
	s_add_i32 s8, s45, 64
	s_min_i32 s8, s8, s14
	s_mul_i32 s8, s8, s42
	s_mov_b32 s9, 0
	v_lshl_add_u64 v[238:239], v[240:241], 0, s[8:9]
	s_add_i32 m0, s22, 0x20080
	v_mfma_f32_16x16x32_f16 v[44:47], v[80:83], v[124:127], v[44:47]
	s_nop 0
	global_load_lds_dwordx4 v[238:239], off
	s_add_i32 s45, s45, 32
	s_add_i32 s41, s41, -1
	s_add_i32 s10, s45, 0x9f
	v_mfma_f32_16x16x32_f16 v[40:43], v[76:79], v[124:127], v[40:43]
	s_cmp_gt_i32 s10, s51
	s_cselect_b32 s11, 2, 0
	s_add_i32 s10, s45, 0x1f1
	s_cmp_le_i32 s10, s51
	s_cselect_b32 s10, 2, 0
	s_and_b32 s10, s10, s4
	v_mfma_f32_16x16x32_f16 v[36:39], v[72:75], v[124:127], v[36:39]
	s_or_b32 s11, s11, s10
	s_lshr_b32 s10, s45, 6
	s_bitcmp1_b32 s39, s10
	s_cselect_b32 s10, 1, 0
	s_lshr_b32 s9, s11, 1
	v_mfma_f32_16x16x32_f16 v[32:35], v[68:71], v[124:127], v[32:35]
	s_or_b32 s10, s10, s9
	s_cmp_le_i32 s45, s15
	s_cselect_b32 s10, s10, 0
	s_cmp_ge_i32 s45, s40
	s_cselect_b32 s10, s10, 0
	s_or_b32 s12, s11, s10
	s_mov_b32 s44, 0
	s_cmp_lg_u32 s41, 0
	s_cbranch_scc1 .Lat_ytop2
	s_branch .Lat_yexit

; template <bool SEL, bool GEN>
; DI void attn_step(const KF& kv, const int kb, const int t, const int lane, const bool selbit,
;                   const LAS float* tabh, const half8 (&q)[2][2], f32x4 (&O)[2][4], const float (&nR)[2], float (&l)[2]) {
;     ...
;   for (int hp = 0; hp < 2; ++hp) {
;     float nm = nR[hp];
;     if (SEL) nm = selbit ? nm : MASKV;
;     const f32x4 c0 = {nm, nm, nm, nm};
; #pragma unroll
;     for (int kt = 0; kt < 2; ++kt) {
;       s[hp][kt] = MFMA16(kv.k[kt][0], q[hp][0], c0);
;       s[hp][kt] = MFMA16(kv.k[kt][1], q[hp][1], s[hp][kt]);
;     }
;   }
;   if (GEN) {
;     const int d0 = t - kb - fq * 4;
; #pragma unroll
;     for (int kt = 0; kt < 2; ++kt)
; #pragma unroll
;       for (int j = 0; j < 4; ++j) {
;         const int dist = d0 - (kt * 16 + j);
;         const bool bad = SEL ? (dist < 0) : ((unsigned)dist >= 512u);
;         const int ix = bad ? 130 : (dist > 128 ? 128 : dist);
; #pragma unroll
;         for (int hp = 0; hp < 2; ++hp) s[hp][kt][j] += tabh[hp * 132 + ix];
;       }
;   }
;   half8 pf[2];
; #pragma unroll
;   for (int hp = 0; hp < 2; ++hp) {
;     f32x4 p0, p1;
; #pragma unroll
;     for (int j = 0; j < 4; ++j) { p0[j] = __builtin_amdgcn_exp2f(s[hp][0][j]); p1[j] = __builtin_amdgcn_exp2f(s[hp][1][j]); }
;     l[hp] += ((p0[0] + p0[1]) + (p0[2] + p0[3])) + ((p1[0] + p1[1]) + (p1[2] + p1[3]));
;     pf[hp] = pack8(p0, p1);
;   }
; #pragma unroll
;   for (int dt = 0; dt < 4; ++dt)
; #pragma unroll
;     for (int hp = 0; hp < 2; ++hp) O[hp][dt] = MFMA16(kv.v[dt], pf[hp], O[hp][dt]);
; DI void attn_phase(const Params& p, const int layer, const int wid_s) {
;     ...
;         asm volatile("s_waitcnt vmcnt(0)" ::: "memory");
;         __syncthreads();
;         RING_ISSUE(0); RING_ISSUE(1);
; #pragma unroll 1
;         for (int si = 0; si < nsteps; ++si) {
;           asm volatile("s_waitcnt vmcnt(1) lgkmcnt(0)" ::: "memory");
;           __builtin_amdgcn_s_barrier();
;           asm volatile("" ::: "memory");
;           RING_ISSUE(si + 2);
;           const int kb = kb0 + si * 32;
;           if (kb > kmax_w || kb < lo_w) continue;
;           if (br == 1 && kb + 31 + 128 <= t0 && __ballot((selmask >> (kb >> 6)) & 1u) == 0ull) continue;
;           LAS unsigned char* slotp = ring + (si % 3) * 8192;
;           KF kv;
; #pragma unroll
;           for (int kt = 0; kt < 2; ++kt)
; #pragma unroll
.Lat_cok_y2:
	s_bitcmp1_b32 s44, 0
	s_cbranch_scc0 .Lat_yb2
	s_waitcnt lgkmcnt(4)
	v_mfma_f32_16x16x32_f16 v[60:63], v[80:83], v[120:123], v[60:63]
	v_add_f32_e32 v214, v214, v198
	v_add_f32_e32 v215, v215, v199
	v_add_f32_e32 v216, v216, v200
	v_mfma_f32_16x16x32_f16 v[56:59], v[76:79], v[120:123], v[56:59]
	v_add_f32_e32 v217, v217, v201
	v_add_f32_e32 v214, v214, v202
	v_add_f32_e32 v215, v215, v203
	v_mfma_f32_16x16x32_f16 v[52:55], v[72:75], v[120:123], v[52:55]
	v_add_f32_e32 v216, v216, v204
	v_add_f32_e32 v217, v217, v205
	v_add_f32_e32 v218, v218, v206
	v_mfma_f32_16x16x32_f16 v[48:51], v[68:71], v[120:123], v[48:51]
	v_add_f32_e32 v219, v219, v207
	v_add_f32_e32 v220, v220, v208
	v_add_f32_e32 v221, v221, v209
	v_mfma_f32_16x16x32_f16 v[44:47], v[80:83], v[124:127], v[44:47]
	v_add_f32_e32 v218, v218, v210
	v_add_f32_e32 v219, v219, v211
	v_add_f32_e32 v220, v220, v212
	v_mfma_f32_16x16x32_f16 v[40:43], v[76:79], v[124:127], v[40:43]
	v_add_f32_e32 v221, v221, v213
	s_add_i32 s8, s45, 64
	s_min_i32 s8, s8, s14
	v_mfma_f32_16x16x32_f16 v[36:39], v[72:75], v[124:127], v[36:39]
	s_mul_i32 s8, s8, s42
	s_mov_b32 s9, 0
	v_lshl_add_u64 v[238:239], v[240:241], 0, s[8:9]
	v_mfma_f32_16x16x32_f16 v[32:35], v[68:71], v[124:127], v[32:35]
	s_add_i32 m0, s22, 0x19880
	s_nop 0
	global_load_lds_dwordx4 v[238:239], off
	s_waitcnt lgkmcnt(0)
	s_and_b32 s44, s12, 2
	s_or_b32 s44, s44, 1
	v_mfma_f32_16x16x32_f16 v[100:103], v[96:99], v[8:11], v[128:131]
	s_add_i32 s45, s45, 32
	s_add_i32 s41, s41, -1
	v_mfma_f32_16x16x32_f16 v[104:107], v[88:91], v[8:11], v[128:131]
	s_add_i32 s10, s45, 0x9f
	s_cmp_gt_i32 s10, s51
	s_cselect_b32 s11, 2, 0
	v_mfma_f32_16x16x32_f16 v[108:111], v[96:99], v[16:19], v[132:135]
	s_add_i32 s10, s45, 0x1f1
	s_cmp_le_i32 s10, s51
	v_mfma_f32_16x16x32_f16 v[112:115], v[88:91], v[16:19], v[132:135]
	s_cselect_b32 s10, 2, 0
	s_and_b32 s10, s10, s4
	s_or_b32 s11, s11, s10
	v_mfma_f32_16x16x32_f16 v[100:103], v[92:95], v[12:15], v[100:103]
	s_lshr_b32 s10, s45, 6
	s_bitcmp1_b32 s39, s10
	v_mfma_f32_16x16x32_f16 v[104:107], v[84:87], v[12:15], v[104:107]
	s_cselect_b32 s10, 1, 0
	s_lshr_b32 s9, s11, 1
	s_or_b32 s10, s10, s9
	v_mfma_f32_16x16x32_f16 v[108:111], v[92:95], v[20:23], v[108:111]
	s_cmp_le_i32 s45, s15
	s_cselect_b32 s10, s10, 0
	v_mfma_f32_16x16x32_f16 v[112:115], v[84:87], v[20:23], v[112:115]
	s_cmp_ge_i32 s45, s40
	s_cselect_b32 s10, s10, 0
	s_or_b32 s12, s11, s10
	ds_read_b128 v[80:83], v65 offset:20480
	ds_read_b128 v[76:79], v65 offset:21504
	ds_read_b128 v[72:75], v65 offset:22528
	ds_read_b128 v[68:71], v65 offset:23552
	s_bitcmp1_b32 s44, 1
	s_cbranch_scc0 .Lat_noga_ya2
	v_add_f32_e32 v100, v100, v222
	v_add_f32_e32 v101, v101, v223
	v_add_f32_e32 v102, v102, v224
	v_add_f32_e32 v103, v103, v225
	v_add_f32_e32 v104, v104, v226
	v_add_f32_e32 v105, v105, v227
	v_add_f32_e32 v106, v106, v228
	v_add_f32_e32 v107, v107, v229
	v_add_f32_e32 v108, v108, v230
	v_add_f32_e32 v109, v109, v231
	v_add_f32_e32 v110, v110, v232
	v_add_f32_e32 v111, v111, v233
	v_add_f32_e32 v112, v112, v234
	v_add_f32_e32 v113, v113, v235
	v_add_f32_e32 v114, v114, v236
	v_add_f32_e32 v115, v115, v237

; template <bool SEL, bool GEN>
; DI void attn_step(const KF& kv, const int kb, const int t, const int lane, const bool selbit,
;                   const LAS float* tabh, const half8 (&q)[2][2], f32x4 (&O)[2][4], const float (&nR)[2], float (&l)[2]) {
;     ...
;   for (int hp = 0; hp < 2; ++hp) {
;     float nm = nR[hp];
;     if (SEL) nm = selbit ? nm : MASKV;
;     const f32x4 c0 = {nm, nm, nm, nm};
; #pragma unroll
;     for (int kt = 0; kt < 2; ++kt) {
;       s[hp][kt] = MFMA16(kv.k[kt][0], q[hp][0], c0);
;       s[hp][kt] = MFMA16(kv.k[kt][1], q[hp][1], s[hp][kt]);
;     }
;   }
;   if (GEN) {
;     const int d0 = t - kb - fq * 4;
; #pragma unroll
;     for (int kt = 0; kt < 2; ++kt)
; #pragma unroll
;       for (int j = 0; j < 4; ++j) {
;         const int dist = d0 - (kt * 16 + j);
;         const bool bad = SEL ? (dist < 0) : ((unsigned)dist >= 512u);
;         const int ix = bad ? 130 : (dist > 128 ? 128 : dist);
; #pragma unroll
;         for (int hp = 0; hp < 2; ++hp) s[hp][kt][j] += tabh[hp * 132 + ix];
;       }
; DI void attn_phase(const Params& p, const int layer, const int wid_s) {
;     ...
;         asm volatile("s_waitcnt vmcnt(0)" ::: "memory");
;         __syncthreads();
;         RING_ISSUE(0); RING_ISSUE(1);
; #pragma unroll 1
;         for (int si = 0; si < nsteps; ++si) {
;           asm volatile("s_waitcnt vmcnt(1) lgkmcnt(0)" ::: "memory");
;           __builtin_amdgcn_s_barrier();
;           asm volatile("" ::: "memory");
;           RING_ISSUE(si + 2);
;           const int kb = kb0 + si * 32;
;           if (kb > kmax_w || kb < lo_w) continue;
;           if (br == 1 && kb + 31 + 128 <= t0 && __ballot((selmask >> (kb >> 6)) & 1u) == 0ull) continue;
;           LAS unsigned char* slotp = ring + (si % 3) * 8192;
;           KF kv;
; #pragma unroll
;           for (int kt = 0; kt < 2; ++kt)
; #pragma unroll
;             for (int ks = 0; ks < 2; ++ks) kv.k[kt][ks] = *(const LAS half8*)(slotp + kread[kt][ks]);
; #pragma unroll
;           for (int dt = 0; dt < 4; ++dt) kv.v[dt] = *(const LAS half8*)(slotp + vread[dt]);
;           if (br == 1) {
;             const bool bit = (selmask >> (kb >> 6)) & 1u;
;             if (kb + 31 + 128 <= t0) attn_step<true, false>(kv, kb, t, lane, bit, tabh, q, O, nRs, l);
;             else attn_step<true, true>(kv, kb, t, lane, bit, tabh, q, O, nRs, l);
;           } else {
.Lat_yb2:
	s_waitcnt lgkmcnt(0)
	s_and_b32 s44, s12, 2
	s_or_b32 s44, s44, 1
	v_mfma_f32_16x16x32_f16 v[100:103], v[96:99], v[8:11], v[128:131]
	s_add_i32 s8, s45, 64
	s_min_i32 s8, s8, s14
	s_mul_i32 s8, s8, s42
	v_mfma_f32_16x16x32_f16 v[104:107], v[88:91], v[8:11], v[128:131]
	s_mov_b32 s9, 0
	v_lshl_add_u64 v[238:239], v[240:241], 0, s[8:9]
	s_add_i32 m0, s22, 0x19880
	s_nop 0
	v_mfma_f32_16x16x32_f16 v[108:111], v[96:99], v[16:19], v[132:135]
	global_load_lds_dwordx4 v[238:239], off
	s_add_i32 s45, s45, 32
	s_add_i32 s41, s41, -1
	v_mfma_f32_16x16x32_f16 v[112:115], v[88:91], v[16:19], v[132:135]
	s_add_i32 s10, s45, 0x9f
	s_cmp_gt_i32 s10, s51
	s_cselect_b32 s11, 2, 0
	s_add_i32 s10, s45, 0x1f1
	v_mfma_f32_16x16x32_f16 v[100:103], v[92:95], v[12:15], v[100:103]
	s_cmp_le_i32 s10, s51
	s_cselect_b32 s10, 2, 0
	s_and_b32 s10, s10, s4
	v_mfma_f32_16x16x32_f16 v[104:107], v[84:87], v[12:15], v[104:107]
	s_or_b32 s11, s11, s10
	s_lshr_b32 s10, s45, 6
	s_bitcmp1_b32 s39, s10
	s_cselect_b32 s10, 1, 0
	v_mfma_f32_16x16x32_f16 v[108:111], v[92:95], v[20:23], v[108:111]
	s_lshr_b32 s9, s11, 1
	s_or_b32 s10, s10, s9
	s_cmp_le_i32 s45, s15
	v_mfma_f32_16x16x32_f16 v[112:115], v[84:87], v[20:23], v[112:115]
	s_cselect_b32 s10, s10, 0
	s_cmp_ge_i32 s45, s40
	s_cselect_b32 s10, s10, 0
	s_or_b32 s12, s11, s10
	ds_read_b128 v[80:83], v65 offset:20480
	ds_read_b128 v[76:79], v65 offset:21504
	ds_read_b128 v[72:75], v65 offset:22528
	ds_read_b128 v[68:71], v65 offset:23552
	s_bitcmp1_b32 s44, 1
	s_cbranch_scc0 .Lat_noga_yb2
	v_add_f32_e32 v100, v100, v222
	v_add_f32_e32 v101, v101, v223
	v_add_f32_e32 v102, v102, v224
	v_add_f32_e32 v103, v103, v225
	v_add_f32_e32 v104, v104, v226
	v_add_f32_e32 v105, v105, v227
	v_add_f32_e32 v106, v106, v228
	v_add_f32_e32 v107, v107, v229
	v_add_f32_e32 v108, v108, v230
	v_add_f32_e32 v109, v109, v231
	v_add_f32_e32 v110, v110, v232
	v_add_f32_e32 v111, v111, v233
	v_add_f32_e32 v112, v112, v234
	v_add_f32_e32 v113, v113, v235
	v_add_f32_e32 v114, v114, v236
	v_add_f32_e32 v115, v115, v237

; #define MFMA16(a, b, c) __builtin_amdgcn_mfma_f32_16x16x32_f16((a), (b), (c), 0, 0, 0)
; #define LAS __attribute__((address_space(3)))
; template <bool SEL, bool GEN>
; DI void attn_step(const KF& kv, const int kb, const int t, const int lane, const bool selbit,
;                   const LAS float* tabh, const half8 (&q)[2][2], f32x4 (&O)[2][4], const float (&nR)[2], float (&l)[2]) {
;     ...
;     for (int j = 0; j < 4; ++j) { p0[j] = __builtin_amdgcn_exp2f(s[hp][0][j]); p1[j] = __builtin_amdgcn_exp2f(s[hp][1][j]); }
;     l[hp] += ((p0[0] + p0[1]) + (p0[2] + p0[3])) + ((p1[0] + p1[1]) + (p1[2] + p1[3]));
;     pf[hp] = pack8(p0, p1);
;   }
; #pragma unroll
;   for (int dt = 0; dt < 4; ++dt)
; #pragma unroll
;     for (int hp = 0; hp < 2; ++hp) O[hp][dt] = MFMA16(kv.v[dt], pf[hp], O[hp][dt]);
; DI void attn_phase(const Params& p, const int layer, const int wid_s) {
;     ...
;         asm volatile("s_waitcnt vmcnt(0)" ::: "memory");
;         __syncthreads();
;         RING_ISSUE(0); RING_ISSUE(1);
; #pragma unroll 1
;         for (int si = 0; si < nsteps; ++si) {
;           asm volatile("s_waitcnt vmcnt(1) lgkmcnt(0)" ::: "memory");
;           __builtin_amdgcn_s_barrier();
;           asm volatile("" ::: "memory");
;           RING_ISSUE(si + 2);
;           const int kb = kb0 + si * 32;
;           if (kb > kmax_w || kb < lo_w) continue;
;           if (br == 1 && kb + 31 + 128 <= t0 && __ballot((selmask >> (kb >> 6)) & 1u) == 0ull) continue;
;           LAS unsigned char* slotp = ring + (si % 3) * 8192;
;           KF kv;
; #pragma unroll
;           for (int kt = 0; kt < 2; ++kt)
; #pragma unroll
;             for (int ks = 0; ks < 2; ++ks) kv.k[kt][ks] = *(const LAS half8*)(slotp + kread[kt][ks]);
; #pragma unroll
;           for (int dt = 0; dt < 4; ++dt) kv.v[dt] = *(const LAS half8*)(slotp + vread[dt]);
;           if (br == 1) {
;             const bool bit = (selmask >> (kb >> 6)) & 1u;
;             if (kb + 31 + 128 <= t0) attn_step<true, false>(kv, kb, t, lane, bit, tabh, q, O, nRs, l);
;             else attn_step<true, true>(kv, kb, t, lane, bit, tabh, q, O, nRs, l);
;           } else {
;             const bool gen = (kb + 31 + 128 > t0) || (kb + 512 <= t0 + 15);
.Lat_yskip2:
	s_bitcmp1_b32 s44, 0
	s_cbranch_scc0 .Lat_yd2
	s_waitcnt lgkmcnt(0)
	v_mfma_f32_16x16x32_f16 v[60:63], v[80:83], v[120:123], v[60:63]
	v_add_f32_e32 v214, v214, v198
	v_add_f32_e32 v215, v215, v199
	v_add_f32_e32 v216, v216, v200
	v_add_f32_e32 v217, v217, v201
	v_add_f32_e32 v214, v214, v202
	v_mfma_f32_16x16x32_f16 v[56:59], v[76:79], v[120:123], v[56:59]
	v_add_f32_e32 v215, v215, v203
	v_add_f32_e32 v216, v216, v204
	v_add_f32_e32 v217, v217, v205
	v_add_f32_e32 v218, v218, v206
	v_add_f32_e32 v219, v219, v207
	v_add_f32_e32 v220, v220, v208
	v_mfma_f32_16x16x32_f16 v[52:55], v[72:75], v[120:123], v[52:55]
	v_add_f32_e32 v221, v221, v209
	v_add_f32_e32 v218, v218, v210
	v_add_f32_e32 v219, v219, v211
	v_add_f32_e32 v220, v220, v212
	v_add_f32_e32 v221, v221, v213
	v_mfma_f32_16x16x32_f16 v[48:51], v[68:71], v[120:123], v[48:51]
	s_add_i32 s8, s45, 64
	s_min_i32 s8, s8, s14
	s_mul_i32 s8, s8, s42
	s_mov_b32 s9, 0
	v_lshl_add_u64 v[238:239], v[240:241], 0, s[8:9]
	s_add_i32 m0, s22, 0x19880
	v_mfma_f32_16x16x32_f16 v[44:47], v[80:83], v[124:127], v[44:47]
	s_nop 0
	global_load_lds_dwordx4 v[238:239], off
	s_add_i32 s45, s45, 32
	s_add_i32 s41, s41, -1
	s_add_i32 s10, s45, 0x9f
	v_mfma_f32_16x16x32_f16 v[40:43], v[76:79], v[124:127], v[40:43]
	s_cmp_gt_i32 s10, s51
	s_cselect_b32 s11, 2, 0
	s_add_i32 s10, s45, 0x1f1
	s_cmp_le_i32 s10, s51
	s_cselect_b32 s10, 2, 0
	s_and_b32 s10, s10, s4
	v_mfma_f32_16x16x32_f16 v[36:39], v[72:75], v[124:127], v[36:39]
	s_or_b32 s11, s11, s10
	s_lshr_b32 s10, s45, 6
	s_bitcmp1_b32 s39, s10
	s_cselect_b32 s10, 1, 0
	s_lshr_b32 s9, s11, 1
	v_mfma_f32_16x16x32_f16 v[32:35], v[68:71], v[124:127], v[32:35]
	s_or_b32 s10, s10, s9
	s_cmp_le_i32 s45, s15
	s_cselect_b32 s10, s10, 0
	s_cmp_ge_i32 s45, s40
	s_cselect_b32 s10, s10, 0
	s_or_b32 s12, s11, s10
	s_mov_b32 s44, 0
	s_cmp_lg_u32 s41, 0
	s_cbranch_scc1 .Lat_ytop3
	s_branch .Lat_yexit

; template <bool SEL, bool GEN>
; DI void attn_step(const KF& kv, const int kb, const int t, const int lane, const bool selbit,
;                   const LAS float* tabh, const half8 (&q)[2][2], f32x4 (&O)[2][4], const float (&nR)[2], float (&l)[2]) {
;     ...
;   for (int hp = 0; hp < 2; ++hp) {
;     float nm = nR[hp];
;     if (SEL) nm = selbit ? nm : MASKV;
;     const f32x4 c0 = {nm, nm, nm, nm};
; #pragma unroll
;     for (int kt = 0; kt < 2; ++kt) {
;       s[hp][kt] = MFMA16(kv.k[kt][0], q[hp][0], c0);
;       s[hp][kt] = MFMA16(kv.k[kt][1], q[hp][1], s[hp][kt]);
;     }
;   }
;   if (GEN) {
;     const int d0 = t - kb - fq * 4;
; #pragma unroll
;     for (int kt = 0; kt < 2; ++kt)
; #pragma unroll
;       for (int j = 0; j < 4; ++j) {
;         const int dist = d0 - (kt * 16 + j);
;         const bool bad = SEL ? (dist < 0) : ((unsigned)dist >= 512u);
;         const int ix = bad ? 130 : (dist > 128 ? 128 : dist);
; #pragma unroll
;         for (int hp = 0; hp < 2; ++hp) s[hp][kt][j] += tabh[hp * 132 + ix];
;       }
;   }
;   half8 pf[2];
; #pragma unroll
;   for (int hp = 0; hp < 2; ++hp) {
;     f32x4 p0, p1;
; #pragma unroll
;     for (int j = 0; j < 4; ++j) { p0[j] = __builtin_amdgcn_exp2f(s[hp][0][j]); p1[j] = __builtin_amdgcn_exp2f(s[hp][1][j]); }
;     l[hp] += ((p0[0] + p0[1]) + (p0[2] + p0[3])) + ((p1[0] + p1[1]) + (p1[2] + p1[3]));
;     pf[hp] = pack8(p0, p1);
;   }
; #pragma unroll
;   for (int dt = 0; dt < 4; ++dt)
; #pragma unroll
;     for (int hp = 0; hp < 2; ++hp) O[hp][dt] = MFMA16(kv.v[dt], pf[hp], O[hp][dt]);
; DI void attn_phase(const Params& p, const int layer, const int wid_s) {
;     ...
;         asm volatile("s_waitcnt vmcnt(0)" ::: "memory");
;         __syncthreads();
;         RING_ISSUE(0); RING_ISSUE(1);
; #pragma unroll 1
;         for (int si = 0; si < nsteps; ++si) {
;           asm volatile("s_waitcnt vmcnt(1) lgkmcnt(0)" ::: "memory");
;           __builtin_amdgcn_s_barrier();
;           asm volatile("" ::: "memory");
;           RING_ISSUE(si + 2);
;           const int kb = kb0 + si * 32;
;           if (kb > kmax_w || kb < lo_w) continue;
;           if (br == 1 && kb + 31 + 128 <= t0 && __ballot((selmask >> (kb >> 6)) & 1u) == 0ull) continue;
;           LAS unsigned char* slotp = ring + (si % 3) * 8192;
;           KF kv;
; #pragma unroll
;           for (int kt = 0; kt < 2; ++kt)
; #pragma unroll
.Lat_cok_y3:
	s_bitcmp1_b32 s44, 0
	s_cbranch_scc0 .Lat_yb3
	s_waitcnt lgkmcnt(4)
	v_mfma_f32_16x16x32_f16 v[60:63], v[80:83], v[120:123], v[60:63]
	v_add_f32_e32 v214, v214, v198
	v_add_f32_e32 v215, v215, v199
	v_add_f32_e32 v216, v216, v200
	v_mfma_f32_16x16x32_f16 v[56:59], v[76:79], v[120:123], v[56:59]
	v_add_f32_e32 v217, v217, v201
	v_add_f32_e32 v214, v214, v202
	v_add_f32_e32 v215, v215, v203
	v_mfma_f32_16x16x32_f16 v[52:55], v[72:75], v[120:123], v[52:55]
	v_add_f32_e32 v216, v216, v204
	v_add_f32_e32 v217, v217, v205
	v_add_f32_e32 v218, v218, v206
	v_mfma_f32_16x16x32_f16 v[48:51], v[68:71], v[120:123], v[48:51]
	v_add_f32_e32 v219, v219, v207
	v_add_f32_e32 v220, v220, v208
	v_add_f32_e32 v221, v221, v209
	v_mfma_f32_16x16x32_f16 v[44:47], v[80:83], v[124:127], v[44:47]
	v_add_f32_e32 v218, v218, v210
	v_add_f32_e32 v219, v219, v211
	v_add_f32_e32 v220, v220, v212
	v_mfma_f32_16x16x32_f16 v[40:43], v[76:79], v[124:127], v[40:43]
	v_add_f32_e32 v221, v221, v213
	s_add_i32 s8, s45, 64
	s_min_i32 s8, s8, s14
	v_mfma_f32_16x16x32_f16 v[36:39], v[72:75], v[124:127], v[36:39]
	s_mul_i32 s8, s8, s42
	s_mov_b32 s9, 0
	v_lshl_add_u64 v[238:239], v[240:241], 0, s[8:9]
	v_mfma_f32_16x16x32_f16 v[32:35], v[68:71], v[124:127], v[32:35]
	s_add_i32 m0, s22, 0x1b880
	s_nop 0
	global_load_lds_dwordx4 v[238:239], off
	s_waitcnt lgkmcnt(0)
	s_and_b32 s44, s12, 2
	s_or_b32 s44, s44, 1
	v_mfma_f32_16x16x32_f16 v[100:103], v[96:99], v[8:11], v[128:131]
	s_add_i32 s45, s45, 32
	s_add_i32 s41, s41, -1
	v_mfma_f32_16x16x32_f16 v[104:107], v[88:91], v[8:11], v[128:131]
	s_add_i32 s10, s45, 0x9f
	s_cmp_gt_i32 s10, s51
	s_cselect_b32 s11, 2, 0
	v_mfma_f32_16x16x32_f16 v[108:111], v[96:99], v[16:19], v[132:135]
	s_add_i32 s10, s45, 0x1f1
	s_cmp_le_i32 s10, s51
	v_mfma_f32_16x16x32_f16 v[112:115], v[88:91], v[16:19], v[132:135]
	s_cselect_b32 s10, 2, 0
	s_and_b32 s10, s10, s4
	s_or_b32 s11, s11, s10
	v_mfma_f32_16x16x32_f16 v[100:103], v[92:95], v[12:15], v[100:103]
	s_lshr_b32 s10, s45, 6
	s_bitcmp1_b32 s39, s10
	v_mfma_f32_16x16x32_f16 v[104:107], v[84:87], v[12:15], v[104:107]
	s_cselect_b32 s10, 1, 0
	s_lshr_b32 s9, s11, 1
	s_or_b32 s10, s10, s9
	v_mfma_f32_16x16x32_f16 v[108:111], v[92:95], v[20:23], v[108:111]
	s_cmp_le_i32 s45, s15
	s_cselect_b32 s10, s10, 0
	v_mfma_f32_16x16x32_f16 v[112:115], v[84:87], v[20:23], v[112:115]
	s_cmp_ge_i32 s45, s40
	s_cselect_b32 s10, s10, 0
	s_or_b32 s12, s11, s10
	ds_read_b128 v[80:83], v65 offset:30720
	ds_read_b128 v[76:79], v65 offset:31744
	ds_read_b128 v[72:75], v65 offset:32768
	ds_read_b128 v[68:71], v65 offset:33792
	s_bitcmp1_b32 s44, 1
	s_cbranch_scc0 .Lat_noga_ya3
	v_add_f32_e32 v100, v100, v222
	v_add_f32_e32 v101, v101, v223
	v_add_f32_e32 v102, v102, v224
	v_add_f32_e32 v103, v103, v225
	v_add_f32_e32 v104, v104, v226
	v_add_f32_e32 v105, v105, v227
	v_add_f32_e32 v106, v106, v228
	v_add_f32_e32 v107, v107, v229
	v_add_f32_e32 v108, v108, v230
	v_add_f32_e32 v109, v109, v231
	v_add_f32_e32 v110, v110, v232
	v_add_f32_e32 v111, v111, v233
	v_add_f32_e32 v112, v112, v234
	v_add_f32_e32 v113, v113, v235
	v_add_f32_e32 v114, v114, v236
	v_add_f32_e32 v115, v115, v237

; template <bool SEL, bool GEN>
; DI void attn_step(const KF& kv, const int kb, const int t, const int lane, const bool selbit,
;                   const LAS float* tabh, const half8 (&q)[2][2], f32x4 (&O)[2][4], const float (&nR)[2], float (&l)[2]) {
;     ...
;   for (int hp = 0; hp < 2; ++hp) {
;     float nm = nR[hp];
;     if (SEL) nm = selbit ? nm : MASKV;
;     const f32x4 c0 = {nm, nm, nm, nm};
; #pragma unroll
;     for (int kt = 0; kt < 2; ++kt) {
;       s[hp][kt] = MFMA16(kv.k[kt][0], q[hp][0], c0);
;       s[hp][kt] = MFMA16(kv.k[kt][1], q[hp][1], s[hp][kt]);
;     }
;   }
;   if (GEN) {
;     const int d0 = t - kb - fq * 4;
; #pragma unroll
;     for (int kt = 0; kt < 2; ++kt)
; #pragma unroll
;       for (int j = 0; j < 4; ++j) {
;         const int dist = d0 - (kt * 16 + j);
;         const bool bad = SEL ? (dist < 0) : ((unsigned)dist >= 512u);
;         const int ix = bad ? 130 : (dist > 128 ? 128 : dist);
; #pragma unroll
;         for (int hp = 0; hp < 2; ++hp) s[hp][kt][j] += tabh[hp * 132 + ix];
;       }
; DI void attn_phase(const Params& p, const int layer, const int wid_s) {
;     ...
;         asm volatile("s_waitcnt vmcnt(0)" ::: "memory");
;         __syncthreads();
;         RING_ISSUE(0); RING_ISSUE(1);
; #pragma unroll 1
;         for (int si = 0; si < nsteps; ++si) {
;           asm volatile("s_waitcnt vmcnt(1) lgkmcnt(0)" ::: "memory");
;           __builtin_amdgcn_s_barrier();
;           asm volatile("" ::: "memory");
;           RING_ISSUE(si + 2);
;           const int kb = kb0 + si * 32;
;           if (kb > kmax_w || kb < lo_w) continue;
;           if (br == 1 && kb + 31 + 128 <= t0 && __ballot((selmask >> (kb >> 6)) & 1u) == 0ull) continue;
;           LAS unsigned char* slotp = ring + (si % 3) * 8192;
;           KF kv;
; #pragma unroll
;           for (int kt = 0; kt < 2; ++kt)
; #pragma unroll
;             for (int ks = 0; ks < 2; ++ks) kv.k[kt][ks] = *(const LAS half8*)(slotp + kread[kt][ks]);
; #pragma unroll
;           for (int dt = 0; dt < 4; ++dt) kv.v[dt] = *(const LAS half8*)(slotp + vread[dt]);
;           if (br == 1) {
;             const bool bit = (selmask >> (kb >> 6)) & 1u;
;             if (kb + 31 + 128 <= t0) attn_step<true, false>(kv, kb, t, lane, bit, tabh, q, O, nRs, l);
;             else attn_step<true, true>(kv, kb, t, lane, bit, tabh, q, O, nRs, l);
;           } else {
.Lat_yb3:
	s_waitcnt lgkmcnt(0)
	s_and_b32 s44, s12, 2
	s_or_b32 s44, s44, 1
	v_mfma_f32_16x16x32_f16 v[100:103], v[96:99], v[8:11], v[128:131]
	s_add_i32 s8, s45, 64
	s_min_i32 s8, s8, s14
	s_mul_i32 s8, s8, s42
	v_mfma_f32_16x16x32_f16 v[104:107], v[88:91], v[8:11], v[128:131]
	s_mov_b32 s9, 0
	v_lshl_add_u64 v[238:239], v[240:241], 0, s[8:9]
	s_add_i32 m0, s22, 0x1b880
	s_nop 0
	v_mfma_f32_16x16x32_f16 v[108:111], v[96:99], v[16:19], v[132:135]
	global_load_lds_dwordx4 v[238:239], off
	s_add_i32 s45, s45, 32
	s_add_i32 s41, s41, -1
	v_mfma_f32_16x16x32_f16 v[112:115], v[88:91], v[16:19], v[132:135]
	s_add_i32 s10, s45, 0x9f
	s_cmp_gt_i32 s10, s51
	s_cselect_b32 s11, 2, 0
	s_add_i32 s10, s45, 0x1f1
	v_mfma_f32_16x16x32_f16 v[100:103], v[92:95], v[12:15], v[100:103]
	s_cmp_le_i32 s10, s51
	s_cselect_b32 s10, 2, 0
	s_and_b32 s10, s10, s4
	v_mfma_f32_16x16x32_f16 v[104:107], v[84:87], v[12:15], v[104:107]
	s_or_b32 s11, s11, s10
	s_lshr_b32 s10, s45, 6
	s_bitcmp1_b32 s39, s10
	s_cselect_b32 s10, 1, 0
	v_mfma_f32_16x16x32_f16 v[108:111], v[92:95], v[20:23], v[108:111]
	s_lshr_b32 s9, s11, 1
	s_or_b32 s10, s10, s9
	s_cmp_le_i32 s45, s15
	v_mfma_f32_16x16x32_f16 v[112:115], v[84:87], v[20:23], v[112:115]
	s_cselect_b32 s10, s10, 0
	s_cmp_ge_i32 s45, s40
	s_cselect_b32 s10, s10, 0
	s_or_b32 s12, s11, s10
	ds_read_b128 v[80:83], v65 offset:30720
	ds_read_b128 v[76:79], v65 offset:31744
	ds_read_b128 v[72:75], v65 offset:32768
	ds_read_b128 v[68:71], v65 offset:33792
	s_bitcmp1_b32 s44, 1
	s_cbranch_scc0 .Lat_noga_yb3
	v_add_f32_e32 v100, v100, v222
	v_add_f32_e32 v101, v101, v223
	v_add_f32_e32 v102, v102, v224
	v_add_f32_e32 v103, v103, v225
	v_add_f32_e32 v104, v104, v226
	v_add_f32_e32 v105, v105, v227
	v_add_f32_e32 v106, v106, v228
	v_add_f32_e32 v107, v107, v229
	v_add_f32_e32 v108, v108, v230
	v_add_f32_e32 v109, v109, v231
	v_add_f32_e32 v110, v110, v232
	v_add_f32_e32 v111, v111, v233
	v_add_f32_e32 v112, v112, v234
	v_add_f32_e32 v113, v113, v235
	v_add_f32_e32 v114, v114, v236
	v_add_f32_e32 v115, v115, v237

; #define MFMA16(a, b, c) __builtin_amdgcn_mfma_f32_16x16x32_f16((a), (b), (c), 0, 0, 0)
; #define LAS __attribute__((address_space(3)))
; template <bool SEL, bool GEN>
; DI void attn_step(const KF& kv, const int kb, const int t, const int lane, const bool selbit,
;                   const LAS float* tabh, const half8 (&q)[2][2], f32x4 (&O)[2][4], const float (&nR)[2], float (&l)[2]) {
;     ...
;     for (int j = 0; j < 4; ++j) { p0[j] = __builtin_amdgcn_exp2f(s[hp][0][j]); p1[j] = __builtin_amdgcn_exp2f(s[hp][1][j]); }
;     l[hp] += ((p0[0] + p0[1]) + (p0[2] + p0[3])) + ((p1[0] + p1[1]) + (p1[2] + p1[3]));
;     pf[hp] = pack8(p0, p1);
;   }
; #pragma unroll
;   for (int dt = 0; dt < 4; ++dt)
; #pragma unroll
;     for (int hp = 0; hp < 2; ++hp) O[hp][dt] = MFMA16(kv.v[dt], pf[hp], O[hp][dt]);
; DI void attn_phase(const Params& p, const int layer, const int wid_s) {
;     ...
;         asm volatile("s_waitcnt vmcnt(0)" ::: "memory");
;         __syncthreads();
;         RING_ISSUE(0); RING_ISSUE(1);
; #pragma unroll 1
;         for (int si = 0; si < nsteps; ++si) {
;           asm volatile("s_waitcnt vmcnt(1) lgkmcnt(0)" ::: "memory");
;           __builtin_amdgcn_s_barrier();
;           asm volatile("" ::: "memory");
;           RING_ISSUE(si + 2);
;           const int kb = kb0 + si * 32;
;           if (kb > kmax_w || kb < lo_w) continue;
;           if (br == 1 && kb + 31 + 128 <= t0 && __ballot((selmask >> (kb >> 6)) & 1u) == 0ull) continue;
;           LAS unsigned char* slotp = ring + (si % 3) * 8192;
;           KF kv;
; #pragma unroll
;           for (int kt = 0; kt < 2; ++kt)
; #pragma unroll
;             for (int ks = 0; ks < 2; ++ks) kv.k[kt][ks] = *(const LAS half8*)(slotp + kread[kt][ks]);
; #pragma unroll
;           for (int dt = 0; dt < 4; ++dt) kv.v[dt] = *(const LAS half8*)(slotp + vread[dt]);
;           if (br == 1) {
;             const bool bit = (selmask >> (kb >> 6)) & 1u;
;             if (kb + 31 + 128 <= t0) attn_step<true, false>(kv, kb, t, lane, bit, tabh, q, O, nRs, l);
;             else attn_step<true, true>(kv, kb, t, lane, bit, tabh, q, O, nRs, l);
;           } else {
;             const bool gen = (kb + 31 + 128 > t0) || (kb + 512 <= t0 + 15);
.Lat_yskip3:
	s_bitcmp1_b32 s44, 0
	s_cbranch_scc0 .Lat_yd3
	s_waitcnt lgkmcnt(0)
	v_mfma_f32_16x16x32_f16 v[60:63], v[80:83], v[120:123], v[60:63]
	v_add_f32_e32 v214, v214, v198
	v_add_f32_e32 v215, v215, v199
	v_add_f32_e32 v216, v216, v200
	v_add_f32_e32 v217, v217, v201
	v_add_f32_e32 v214, v214, v202
	v_mfma_f32_16x16x32_f16 v[56:59], v[76:79], v[120:123], v[56:59]
	v_add_f32_e32 v215, v215, v203
	v_add_f32_e32 v216, v216, v204
	v_add_f32_e32 v217, v217, v205
	v_add_f32_e32 v218, v218, v206
	v_add_f32_e32 v219, v219, v207
	v_add_f32_e32 v220, v220, v208
	v_mfma_f32_16x16x32_f16 v[52:55], v[72:75], v[120:123], v[52:55]
	v_add_f32_e32 v221, v221, v209
	v_add_f32_e32 v218, v218, v210
	v_add_f32_e32 v219, v219, v211
	v_add_f32_e32 v220, v220, v212
	v_add_f32_e32 v221, v221, v213
	v_mfma_f32_16x16x32_f16 v[48:51], v[68:71], v[120:123], v[48:51]
	s_add_i32 s8, s45, 64
	s_min_i32 s8, s8, s14
	s_mul_i32 s8, s8, s42
	s_mov_b32 s9, 0
	v_lshl_add_u64 v[238:239], v[240:241], 0, s[8:9]
	s_add_i32 m0, s22, 0x1b880
	v_mfma_f32_16x16x32_f16 v[44:47], v[80:83], v[124:127], v[44:47]
	s_nop 0
	global_load_lds_dwordx4 v[238:239], off
	s_add_i32 s45, s45, 32
	s_add_i32 s41, s41, -1
	s_add_i32 s10, s45, 0x9f
	v_mfma_f32_16x16x32_f16 v[40:43], v[76:79], v[124:127], v[40:43]
	s_cmp_gt_i32 s10, s51
	s_cselect_b32 s11, 2, 0
	s_add_i32 s10, s45, 0x1f1
	s_cmp_le_i32 s10, s51
	s_cselect_b32 s10, 2, 0
	s_and_b32 s10, s10, s4
	v_mfma_f32_16x16x32_f16 v[36:39], v[72:75], v[124:127], v[36:39]
	s_or_b32 s11, s11, s10
	s_lshr_b32 s10, s45, 6
	s_bitcmp1_b32 s39, s10
	s_cselect_b32 s10, 1, 0
	s_lshr_b32 s9, s11, 1
	v_mfma_f32_16x16x32_f16 v[32:35], v[68:71], v[124:127], v[32:35]
	s_or_b32 s10, s10, s9
	s_cmp_le_i32 s45, s15
	s_cselect_b32 s10, s10, 0
	s_cmp_ge_i32 s45, s40
	s_cselect_b32 s10, s10, 0
	s_or_b32 s12, s11, s10
	s_mov_b32 s44, 0
	s_cmp_lg_u32 s41, 0
	s_cbranch_scc1 .Lat_ytop
	s_branch .Lat_yexit
